# GEMM K-loops: issue the global->LDS DMA loads before the LDS reads in every load part (longer landing window for far misses)
# speedup vs baseline: 1.0012x; 1.0012x over previous
.LBB0_261:
	s_add_u32 s0, s76, 0xfff80080
	s_addc_u32 s1, s77, -1
	s_and_b64 s[84:85], s[84:85], exec
	s_cselect_b32 vcc_hi, s22, s1
	s_cselect_b32 vcc_lo, s23, s0
	s_cselect_b32 s85, s49, s58
	s_cselect_b32 s84, s57, s51
	s_add_i32 s0, 0, 0x10000
	s_add_i32 s1, 0, 0x14000
	v_add_u32_e32 v174, s1, v176
	ds_read_b128 v[162:165], v174
	ds_read_b128 v[166:169], v174 offset:1024
	ds_read_b128 v[170:173], v174 offset:2048
	ds_read_b128 v[178:181], v174 offset:3072
	v_lshl_add_u64 v[174:175], s[76:77], 0, v[138:139]
	s_add_i32 m0, s21, 0xc000
	s_nop 0
	global_load_lds_dwordx4 v[174:175], off
	v_lshl_add_u64 v[174:175], s[76:77], 0, v[140:141]
	s_add_i32 m0, s21, 0xe000
	s_nop 0
	global_load_lds_dwordx4 v[174:175], off
	v_add_u32_e32 v158, s0, v176
	ds_read_b128 v[146:149], v158
	ds_read_b128 v[150:153], v158 offset:1024
	ds_read_b128 v[154:157], v158 offset:2048
	ds_read_b128 v[158:161], v158 offset:3072
	ds_read_b128 v[182:185], v177
	ds_read_b128 v[186:189], v177 offset:1024
	ds_read_b128 v[190:193], v177 offset:2048
	ds_read_b128 v[204:207], v177 offset:3072
	ds_read_b128 v[208:211], v177 offset:4096
	ds_read_b128 v[212:215], v177 offset:5120
	ds_read_b128 v[216:219], v177 offset:6144
	ds_read_b128 v[220:223], v177 offset:7168
	s_waitcnt vmcnt(8)
	s_waitcnt lgkmcnt(0)
	s_barrier
	s_setprio 1
	s_waitcnt lgkmcnt(0)
	v_mfma_f32_16x16x32_bf16 v[126:129], v[146:149], v[182:185], v[126:129]
	v_mfma_f32_16x16x32_bf16 v[122:125], v[154:157], v[182:185], v[122:125]
	v_mfma_f32_16x16x32_bf16 v[110:113], v[146:149], v[190:193], v[110:113]
	v_mfma_f32_16x16x32_bf16 v[106:109], v[154:157], v[190:193], v[106:109]
	v_mfma_f32_16x16x32_bf16 v[94:97], v[146:149], v[208:211], v[94:97]
	v_mfma_f32_16x16x32_bf16 v[90:93], v[154:157], v[208:211], v[90:93]
	v_mfma_f32_16x16x32_bf16 v[78:81], v[146:149], v[216:219], v[78:81]
	v_mfma_f32_16x16x32_bf16 v[74:77], v[154:157], v[216:219], v[74:77]
	v_mfma_f32_16x16x32_bf16 v[126:129], v[150:153], v[186:189], v[126:129]
	v_mfma_f32_16x16x32_bf16 v[122:125], v[158:161], v[186:189], v[122:125]
	v_mfma_f32_16x16x32_bf16 v[110:113], v[150:153], v[204:207], v[110:113]
	v_mfma_f32_16x16x32_bf16 v[106:109], v[158:161], v[204:207], v[106:109]
	v_mfma_f32_16x16x32_bf16 v[94:97], v[150:153], v[212:215], v[94:97]
	v_mfma_f32_16x16x32_bf16 v[90:93], v[158:161], v[212:215], v[90:93]
	v_mfma_f32_16x16x32_bf16 v[78:81], v[150:153], v[220:223], v[78:81]
	v_mfma_f32_16x16x32_bf16 v[74:77], v[158:161], v[220:223], v[74:77]
	s_setprio 0
	s_setprio 1
	v_mfma_f32_16x16x32_bf16 v[118:121], v[162:165], v[182:185], v[118:121]
	v_mfma_f32_16x16x32_bf16 v[114:117], v[170:173], v[182:185], v[114:117]
	v_mfma_f32_16x16x32_bf16 v[102:105], v[162:165], v[190:193], v[102:105]
	v_mfma_f32_16x16x32_bf16 v[98:101], v[170:173], v[190:193], v[98:101]
	v_mfma_f32_16x16x32_bf16 v[86:89], v[162:165], v[208:211], v[86:89]
	v_mfma_f32_16x16x32_bf16 v[82:85], v[170:173], v[208:211], v[82:85]
	v_mfma_f32_16x16x32_bf16 v[70:73], v[162:165], v[216:219], v[70:73]
	v_mfma_f32_16x16x32_bf16 v[66:69], v[170:173], v[216:219], v[66:69]
	v_mfma_f32_16x16x32_bf16 v[118:121], v[166:169], v[186:189], v[118:121]
	v_mfma_f32_16x16x32_bf16 v[114:117], v[178:181], v[186:189], v[114:117]
	v_mfma_f32_16x16x32_bf16 v[102:105], v[166:169], v[204:207], v[102:105]
	v_mfma_f32_16x16x32_bf16 v[98:101], v[178:181], v[204:207], v[98:101]
	v_mfma_f32_16x16x32_bf16 v[86:89], v[166:169], v[212:215], v[86:89]
	v_mfma_f32_16x16x32_bf16 v[82:85], v[178:181], v[212:215], v[82:85]
	v_mfma_f32_16x16x32_bf16 v[70:73], v[166:169], v[220:223], v[70:73]
	v_mfma_f32_16x16x32_bf16 v[66:69], v[178:181], v[220:223], v[66:69]
	s_setprio 0
	s_barrier
	s_add_i32 s0, s0, s20
	v_lshl_add_u64 v[174:175], s[84:85], 0, v[132:133]
	s_mov_b32 m0, s0
	s_nop 0
	global_load_lds_dwordx4 v[174:175], off
	s_add_i32 m0, s0, 0x2000
	s_add_u32 s94, s84, 0x80000
	v_lshl_add_u64 v[224:225], s[84:85], 0, v[130:131]
	s_addc_u32 s95, s85, 0
	s_add_i32 s0, s1, s20
	global_load_lds_dwordx4 v[224:225], off
	v_lshl_add_u64 v[226:227], s[94:95], 0, v[132:133]
	s_mov_b32 m0, s0
	v_lshl_add_u64 v[228:229], vcc, 0, v[130:131]
	global_load_lds_dwordx4 v[226:227], off
	v_lshl_add_u64 v[226:227], s[94:95], 0, v[130:131]
	s_add_i32 m0, s0, 0x2000
	s_nop 0
	global_load_lds_dwordx4 v[226:227], off
	v_lshl_add_u64 v[226:227], vcc, 0, v[132:133]
	s_mov_b32 m0, s21
	s_nop 0
	global_load_lds_dwordx4 v[226:227], off
	s_mov_b32 m0, s26
	s_nop 0
	global_load_lds_dwordx4 v[228:229], off
	ds_read_b128 v[182:185], v177 offset:16384
	ds_read_b128 v[186:189], v177 offset:17408
	ds_read_b128 v[190:193], v177 offset:18432
	ds_read_b128 v[204:207], v177 offset:19456
	ds_read_b128 v[208:211], v177 offset:20480
	ds_read_b128 v[212:215], v177 offset:21504
	ds_read_b128 v[216:219], v177 offset:22528
	ds_read_b128 v[220:223], v177 offset:23552
	s_waitcnt vmcnt(8)
	s_waitcnt lgkmcnt(0)
	s_barrier
	s_setprio 1
	s_waitcnt lgkmcnt(0)
	v_mfma_f32_16x16x32_bf16 v[62:65], v[146:149], v[182:185], v[62:65]
	v_mfma_f32_16x16x32_bf16 v[58:61], v[154:157], v[182:185], v[58:61]
	v_mfma_f32_16x16x32_bf16 v[46:49], v[146:149], v[190:193], v[46:49]
	v_mfma_f32_16x16x32_bf16 v[42:45], v[154:157], v[190:193], v[42:45]
	v_mfma_f32_16x16x32_bf16 v[30:33], v[146:149], v[208:211], v[30:33]
	v_mfma_f32_16x16x32_bf16 v[26:29], v[154:157], v[208:211], v[26:29]
	v_mfma_f32_16x16x32_bf16 v[14:17], v[146:149], v[216:219], v[14:17]
	v_mfma_f32_16x16x32_bf16 v[10:13], v[154:157], v[216:219], v[10:13]
	v_mfma_f32_16x16x32_bf16 v[62:65], v[150:153], v[186:189], v[62:65]
	v_mfma_f32_16x16x32_bf16 v[58:61], v[158:161], v[186:189], v[58:61]
	v_mfma_f32_16x16x32_bf16 v[46:49], v[150:153], v[204:207], v[46:49]
	v_mfma_f32_16x16x32_bf16 v[42:45], v[158:161], v[204:207], v[42:45]
	v_mfma_f32_16x16x32_bf16 v[30:33], v[150:153], v[212:215], v[30:33]
	v_mfma_f32_16x16x32_bf16 v[26:29], v[158:161], v[212:215], v[26:29]
	v_mfma_f32_16x16x32_bf16 v[14:17], v[150:153], v[220:223], v[14:17]
	v_mfma_f32_16x16x32_bf16 v[10:13], v[158:161], v[220:223], v[10:13]
	s_setprio 0
	s_setprio 1
	v_mfma_f32_16x16x32_bf16 v[54:57], v[162:165], v[182:185], v[54:57]
	v_mfma_f32_16x16x32_bf16 v[50:53], v[170:173], v[182:185], v[50:53]
	v_mfma_f32_16x16x32_bf16 v[38:41], v[162:165], v[190:193], v[38:41]
	v_mfma_f32_16x16x32_bf16 v[34:37], v[170:173], v[190:193], v[34:37]
	v_mfma_f32_16x16x32_bf16 v[22:25], v[162:165], v[208:211], v[22:25]
	v_mfma_f32_16x16x32_bf16 v[18:21], v[170:173], v[208:211], v[18:21]
	v_mfma_f32_16x16x32_bf16 v[6:9], v[162:165], v[216:219], v[6:9]
	v_mfma_f32_16x16x32_bf16 v[2:5], v[170:173], v[216:219], v[2:5]
	v_mfma_f32_16x16x32_bf16 v[54:57], v[166:169], v[186:189], v[54:57]
	v_mfma_f32_16x16x32_bf16 v[50:53], v[178:181], v[186:189], v[50:53]
	v_mfma_f32_16x16x32_bf16 v[38:41], v[166:169], v[204:207], v[38:41]
	v_mfma_f32_16x16x32_bf16 v[34:37], v[178:181], v[204:207], v[34:37]
	v_mfma_f32_16x16x32_bf16 v[22:25], v[166:169], v[212:215], v[22:25]
	v_mfma_f32_16x16x32_bf16 v[18:21], v[178:181], v[212:215], v[18:21]
	v_mfma_f32_16x16x32_bf16 v[6:9], v[166:169], v[220:223], v[6:9]
	v_mfma_f32_16x16x32_bf16 v[2:5], v[178:181], v[220:223], v[2:5]
	s_setprio 0
	s_barrier
	s_add_i32 s0, 0, 0x18000
	s_add_i32 s1, 0, 0x1c000
	s_add_u32 s94, vcc_lo, 0x80000
	s_addc_u32 s95, vcc_hi, 0
	s_mov_b32 m0, s27
	v_lshl_add_u64 v[230:231], s[94:95], 0, v[132:133]
	global_load_lds_dwordx4 v[230:231], off
	v_lshl_add_u64 v[230:231], s[94:95], 0, v[130:131]
	s_mov_b32 m0, s29
	s_nop 0
	global_load_lds_dwordx4 v[230:231], off
	v_add_u32_e32 v158, s0, v176
	v_add_u32_e32 v178, s1, v176
	ds_read_b128 v[146:149], v158
	ds_read_b128 v[150:153], v158 offset:1024
	ds_read_b128 v[154:157], v158 offset:2048
	ds_read_b128 v[158:161], v158 offset:3072
	ds_read_b128 v[162:165], v178
	ds_read_b128 v[166:169], v178 offset:1024
	ds_read_b128 v[170:173], v178 offset:2048
	ds_read_b128 v[178:181], v178 offset:3072
	ds_read_b128 v[182:185], v177 offset:32768
	ds_read_b128 v[186:189], v177 offset:33792
	ds_read_b128 v[190:193], v177 offset:34816
	ds_read_b128 v[204:207], v177 offset:35840
	ds_read_b128 v[208:211], v177 offset:36864
	ds_read_b128 v[212:215], v177 offset:37888
	ds_read_b128 v[216:219], v177 offset:38912
	ds_read_b128 v[220:223], v177 offset:39936
	s_waitcnt vmcnt(8)
	s_waitcnt lgkmcnt(0)
	s_barrier
	s_setprio 1
	s_waitcnt lgkmcnt(0)
	v_mfma_f32_16x16x32_bf16 v[126:129], v[146:149], v[182:185], v[126:129]
	v_mfma_f32_16x16x32_bf16 v[122:125], v[154:157], v[182:185], v[122:125]
	v_mfma_f32_16x16x32_bf16 v[110:113], v[146:149], v[190:193], v[110:113]
	v_mfma_f32_16x16x32_bf16 v[106:109], v[154:157], v[190:193], v[106:109]
	v_mfma_f32_16x16x32_bf16 v[94:97], v[146:149], v[208:211], v[94:97]
	v_mfma_f32_16x16x32_bf16 v[90:93], v[154:157], v[208:211], v[90:93]
	v_mfma_f32_16x16x32_bf16 v[78:81], v[146:149], v[216:219], v[78:81]
	v_mfma_f32_16x16x32_bf16 v[74:77], v[154:157], v[216:219], v[74:77]
	v_mfma_f32_16x16x32_bf16 v[126:129], v[150:153], v[186:189], v[126:129]
	v_mfma_f32_16x16x32_bf16 v[122:125], v[158:161], v[186:189], v[122:125]
	v_mfma_f32_16x16x32_bf16 v[110:113], v[150:153], v[204:207], v[110:113]
	v_mfma_f32_16x16x32_bf16 v[106:109], v[158:161], v[204:207], v[106:109]
	v_mfma_f32_16x16x32_bf16 v[94:97], v[150:153], v[212:215], v[94:97]
	v_mfma_f32_16x16x32_bf16 v[90:93], v[158:161], v[212:215], v[90:93]
	v_mfma_f32_16x16x32_bf16 v[78:81], v[150:153], v[220:223], v[78:81]
	v_mfma_f32_16x16x32_bf16 v[74:77], v[158:161], v[220:223], v[74:77]
	s_setprio 0
	s_setprio 1
	v_mfma_f32_16x16x32_bf16 v[118:121], v[162:165], v[182:185], v[118:121]
	v_mfma_f32_16x16x32_bf16 v[114:117], v[170:173], v[182:185], v[114:117]
	v_mfma_f32_16x16x32_bf16 v[102:105], v[162:165], v[190:193], v[102:105]
	v_mfma_f32_16x16x32_bf16 v[98:101], v[170:173], v[190:193], v[98:101]
	v_mfma_f32_16x16x32_bf16 v[86:89], v[162:165], v[208:211], v[86:89]
	v_mfma_f32_16x16x32_bf16 v[82:85], v[170:173], v[208:211], v[82:85]
	v_mfma_f32_16x16x32_bf16 v[70:73], v[162:165], v[216:219], v[70:73]
	v_mfma_f32_16x16x32_bf16 v[66:69], v[170:173], v[216:219], v[66:69]
	v_mfma_f32_16x16x32_bf16 v[118:121], v[166:169], v[186:189], v[118:121]
	v_mfma_f32_16x16x32_bf16 v[114:117], v[178:181], v[186:189], v[114:117]
	v_mfma_f32_16x16x32_bf16 v[102:105], v[166:169], v[204:207], v[102:105]
	v_mfma_f32_16x16x32_bf16 v[98:101], v[178:181], v[204:207], v[98:101]
	v_mfma_f32_16x16x32_bf16 v[86:89], v[166:169], v[212:215], v[86:89]
	v_mfma_f32_16x16x32_bf16 v[82:85], v[178:181], v[212:215], v[82:85]
	v_mfma_f32_16x16x32_bf16 v[70:73], v[166:169], v[220:223], v[70:73]
	v_mfma_f32_16x16x32_bf16 v[66:69], v[178:181], v[220:223], v[66:69]
	s_setprio 0
	s_barrier
	s_add_i32 s0, s0, s20
	v_lshl_add_u64 v[174:175], v[174:175], 0, s[82:83]
	s_mov_b32 m0, s0
	s_nop 0
	global_load_lds_dwordx4 v[174:175], off
	s_add_i32 m0, s0, 0x2000
	s_add_u32 s84, s84, 0x80080
	v_lshl_add_u64 v[174:175], v[224:225], 0, s[82:83]
	s_addc_u32 s85, s85, 0
	s_add_i32 s0, s1, s20
	global_load_lds_dwordx4 v[174:175], off
	v_lshl_add_u64 v[174:175], s[84:85], 0, v[132:133]
	s_mov_b32 m0, s0
	s_nop 0
	global_load_lds_dwordx4 v[174:175], off
	v_lshl_add_u64 v[174:175], s[84:85], 0, v[130:131]
	s_add_i32 m0, s0, 0x2000
	s_nop 0
	global_load_lds_dwordx4 v[174:175], off
	v_lshl_add_u64 v[174:175], v[226:227], 0, s[82:83]
	s_mov_b32 m0, s40
	s_nop 0
	global_load_lds_dwordx4 v[174:175], off
	v_lshl_add_u64 v[174:175], v[228:229], 0, s[82:83]
	s_mov_b32 m0, s41
	s_nop 0
	global_load_lds_dwordx4 v[174:175], off
	ds_read_b128 v[182:185], v177 offset:49152
	ds_read_b128 v[186:189], v177 offset:50176
	ds_read_b128 v[190:193], v177 offset:51200
	ds_read_b128 v[204:207], v177 offset:52224
	ds_read_b128 v[208:211], v177 offset:53248
	ds_read_b128 v[212:215], v177 offset:54272
	ds_read_b128 v[216:219], v177 offset:55296
	ds_read_b128 v[220:223], v177 offset:56320
	s_waitcnt vmcnt(8)
	s_waitcnt lgkmcnt(0)
	s_barrier
	s_setprio 1
	s_waitcnt lgkmcnt(0)
	v_mfma_f32_16x16x32_bf16 v[62:65], v[146:149], v[182:185], v[62:65]
	v_mfma_f32_16x16x32_bf16 v[58:61], v[154:157], v[182:185], v[58:61]
	v_mfma_f32_16x16x32_bf16 v[46:49], v[146:149], v[190:193], v[46:49]
	v_mfma_f32_16x16x32_bf16 v[42:45], v[154:157], v[190:193], v[42:45]
	v_mfma_f32_16x16x32_bf16 v[30:33], v[146:149], v[208:211], v[30:33]
	v_mfma_f32_16x16x32_bf16 v[26:29], v[154:157], v[208:211], v[26:29]
	v_mfma_f32_16x16x32_bf16 v[14:17], v[146:149], v[216:219], v[14:17]
	v_mfma_f32_16x16x32_bf16 v[10:13], v[154:157], v[216:219], v[10:13]
	v_mfma_f32_16x16x32_bf16 v[62:65], v[150:153], v[186:189], v[62:65]
	v_mfma_f32_16x16x32_bf16 v[58:61], v[158:161], v[186:189], v[58:61]
	v_mfma_f32_16x16x32_bf16 v[46:49], v[150:153], v[204:207], v[46:49]
	v_mfma_f32_16x16x32_bf16 v[42:45], v[158:161], v[204:207], v[42:45]
	v_mfma_f32_16x16x32_bf16 v[30:33], v[150:153], v[212:215], v[30:33]
	v_mfma_f32_16x16x32_bf16 v[26:29], v[158:161], v[212:215], v[26:29]
	v_mfma_f32_16x16x32_bf16 v[14:17], v[150:153], v[220:223], v[14:17]
	v_mfma_f32_16x16x32_bf16 v[10:13], v[158:161], v[220:223], v[10:13]
	s_setprio 0
	s_setprio 1
	v_mfma_f32_16x16x32_bf16 v[54:57], v[162:165], v[182:185], v[54:57]
	v_mfma_f32_16x16x32_bf16 v[50:53], v[170:173], v[182:185], v[50:53]
	v_mfma_f32_16x16x32_bf16 v[38:41], v[162:165], v[190:193], v[38:41]
	v_mfma_f32_16x16x32_bf16 v[34:37], v[170:173], v[190:193], v[34:37]
	v_mfma_f32_16x16x32_bf16 v[22:25], v[162:165], v[208:211], v[22:25]
	v_mfma_f32_16x16x32_bf16 v[18:21], v[170:173], v[208:211], v[18:21]
	v_mfma_f32_16x16x32_bf16 v[6:9], v[162:165], v[216:219], v[6:9]
	v_mfma_f32_16x16x32_bf16 v[2:5], v[170:173], v[216:219], v[2:5]
	v_mfma_f32_16x16x32_bf16 v[54:57], v[166:169], v[186:189], v[54:57]
	v_mfma_f32_16x16x32_bf16 v[50:53], v[178:181], v[186:189], v[50:53]
	v_mfma_f32_16x16x32_bf16 v[38:41], v[166:169], v[204:207], v[38:41]
	v_mfma_f32_16x16x32_bf16 v[34:37], v[178:181], v[204:207], v[34:37]
	v_mfma_f32_16x16x32_bf16 v[22:25], v[166:169], v[212:215], v[22:25]
	v_mfma_f32_16x16x32_bf16 v[18:21], v[178:181], v[212:215], v[18:21]
	v_mfma_f32_16x16x32_bf16 v[6:9], v[166:169], v[220:223], v[6:9]
	v_mfma_f32_16x16x32_bf16 v[2:5], v[178:181], v[220:223], v[2:5]
	s_setprio 0
	s_barrier
	s_add_i32 s65, s65, 2
	s_add_u32 s76, s76, 0x100
	s_addc_u32 s77, s77, 0
	s_add_u32 s51, s51, 0x100
	s_addc_u32 s58, s58, 0
	s_cmp_gt_u32 s65, 29
	s_cbranch_scc1 .LBB0_264

.LBB0_285:
	s_add_u32 s0, s76, 0xfff80080
	s_addc_u32 s1, s77, -1
	s_and_b64 s[70:71], s[70:71], exec
	s_cselect_b32 vcc_hi, s21, s1
	s_cselect_b32 vcc_lo, s22, s0
	s_cselect_b32 s71, s23, s41
	s_cselect_b32 s70, s39, s7
	s_add_i32 s0, 0, 0x10000
	s_add_i32 s1, 0, 0x14000
	v_lshl_add_u64 v[220:221], s[76:77], 0, v[170:171]
	s_add_i32 m0, s67, 0xc000
	s_nop 0
	global_load_lds_dwordx4 v[220:221], off
	v_lshl_add_u64 v[220:221], s[76:77], 0, v[172:173]
	s_add_i32 m0, s67, 0xe000
	s_nop 0
	global_load_lds_dwordx4 v[220:221], off
	v_add_u32_e32 v146, s0, v1
	v_add_u32_e32 v174, s1, v1
	ds_read_b128 v[134:137], v146
	ds_read_b128 v[138:141], v146 offset:1024
	ds_read_b128 v[142:145], v146 offset:2048
	ds_read_b128 v[146:149], v146 offset:3072
	ds_read_b128 v[150:153], v174
	ds_read_b128 v[154:157], v174 offset:1024
	ds_read_b128 v[158:161], v174 offset:2048
	ds_read_b128 v[174:177], v174 offset:3072
	ds_read_b128 v[178:181], v222
	ds_read_b128 v[182:185], v222 offset:1024
	ds_read_b128 v[186:189], v222 offset:2048
	ds_read_b128 v[190:193], v222 offset:3072
	ds_read_b128 v[204:207], v222 offset:4096
	ds_read_b128 v[208:211], v222 offset:5120
	ds_read_b128 v[212:215], v222 offset:6144
	ds_read_b128 v[216:219], v222 offset:7168
	s_waitcnt vmcnt(8)
	s_waitcnt lgkmcnt(0)
	s_barrier
	s_setprio 1
	s_waitcnt lgkmcnt(0)
	v_mfma_f32_16x16x32_bf16 v[126:129], v[134:137], v[178:181], v[126:129]
	v_mfma_f32_16x16x32_bf16 v[122:125], v[142:145], v[178:181], v[122:125]
	v_mfma_f32_16x16x32_bf16 v[110:113], v[134:137], v[186:189], v[110:113]
	v_mfma_f32_16x16x32_bf16 v[106:109], v[142:145], v[186:189], v[106:109]
	v_mfma_f32_16x16x32_bf16 v[94:97], v[134:137], v[204:207], v[94:97]
	v_mfma_f32_16x16x32_bf16 v[90:93], v[142:145], v[204:207], v[90:93]
	v_mfma_f32_16x16x32_bf16 v[78:81], v[134:137], v[212:215], v[78:81]
	v_mfma_f32_16x16x32_bf16 v[74:77], v[142:145], v[212:215], v[74:77]
	v_mfma_f32_16x16x32_bf16 v[126:129], v[138:141], v[182:185], v[126:129]
	v_mfma_f32_16x16x32_bf16 v[122:125], v[146:149], v[182:185], v[122:125]
	v_mfma_f32_16x16x32_bf16 v[110:113], v[138:141], v[190:193], v[110:113]
	v_mfma_f32_16x16x32_bf16 v[106:109], v[146:149], v[190:193], v[106:109]
	v_mfma_f32_16x16x32_bf16 v[94:97], v[138:141], v[208:211], v[94:97]
	v_mfma_f32_16x16x32_bf16 v[90:93], v[146:149], v[208:211], v[90:93]
	v_mfma_f32_16x16x32_bf16 v[78:81], v[138:141], v[216:219], v[78:81]
	v_mfma_f32_16x16x32_bf16 v[74:77], v[146:149], v[216:219], v[74:77]
	s_setprio 0
	s_setprio 1
	v_mfma_f32_16x16x32_bf16 v[118:121], v[150:153], v[178:181], v[118:121]
	v_mfma_f32_16x16x32_bf16 v[114:117], v[158:161], v[178:181], v[114:117]
	v_mfma_f32_16x16x32_bf16 v[102:105], v[150:153], v[186:189], v[102:105]
	v_mfma_f32_16x16x32_bf16 v[98:101], v[158:161], v[186:189], v[98:101]
	v_mfma_f32_16x16x32_bf16 v[86:89], v[150:153], v[204:207], v[86:89]
	v_mfma_f32_16x16x32_bf16 v[82:85], v[158:161], v[204:207], v[82:85]
	v_mfma_f32_16x16x32_bf16 v[70:73], v[150:153], v[212:215], v[70:73]
	v_mfma_f32_16x16x32_bf16 v[66:69], v[158:161], v[212:215], v[66:69]
	v_mfma_f32_16x16x32_bf16 v[118:121], v[154:157], v[182:185], v[118:121]
	v_mfma_f32_16x16x32_bf16 v[114:117], v[174:177], v[182:185], v[114:117]
	v_mfma_f32_16x16x32_bf16 v[102:105], v[154:157], v[190:193], v[102:105]
	v_mfma_f32_16x16x32_bf16 v[98:101], v[174:177], v[190:193], v[98:101]
	v_mfma_f32_16x16x32_bf16 v[86:89], v[154:157], v[208:211], v[86:89]
	v_mfma_f32_16x16x32_bf16 v[82:85], v[174:177], v[208:211], v[82:85]
	v_mfma_f32_16x16x32_bf16 v[70:73], v[154:157], v[216:219], v[70:73]
	v_mfma_f32_16x16x32_bf16 v[66:69], v[174:177], v[216:219], v[66:69]
	s_setprio 0
	s_barrier
	s_add_i32 s0, s0, s54
	v_lshl_add_u64 v[220:221], s[70:71], 0, v[164:165]
	s_mov_b32 m0, s0
	s_nop 0
	global_load_lds_dwordx4 v[220:221], off
	s_add_i32 m0, s0, 0x2000
	s_add_u32 s44, s70, 0x80000
	v_lshl_add_u64 v[224:225], s[70:71], 0, v[162:163]
	s_addc_u32 s45, s71, 0
	s_add_i32 s0, s1, s54
	global_load_lds_dwordx4 v[224:225], off
	v_lshl_add_u64 v[226:227], s[44:45], 0, v[164:165]
	s_mov_b32 m0, s0
	v_lshl_add_u64 v[228:229], vcc, 0, v[162:163]
	global_load_lds_dwordx4 v[226:227], off
	v_lshl_add_u64 v[226:227], s[44:45], 0, v[162:163]
	s_add_i32 m0, s0, 0x2000
	s_nop 0
	global_load_lds_dwordx4 v[226:227], off
	v_lshl_add_u64 v[226:227], vcc, 0, v[164:165]
	s_mov_b32 m0, s67
	s_nop 0
	global_load_lds_dwordx4 v[226:227], off
	s_mov_b32 m0, s68
	s_nop 0
	global_load_lds_dwordx4 v[228:229], off
	ds_read_b128 v[178:181], v222 offset:16384
	ds_read_b128 v[182:185], v222 offset:17408
	ds_read_b128 v[186:189], v222 offset:18432
	ds_read_b128 v[190:193], v222 offset:19456
	ds_read_b128 v[204:207], v222 offset:20480
	ds_read_b128 v[208:211], v222 offset:21504
	ds_read_b128 v[212:215], v222 offset:22528
	ds_read_b128 v[216:219], v222 offset:23552
	s_waitcnt vmcnt(8)
	s_waitcnt lgkmcnt(0)
	s_barrier
	s_setprio 1
	s_waitcnt lgkmcnt(0)
	v_mfma_f32_16x16x32_bf16 v[62:65], v[134:137], v[178:181], v[62:65]
	v_mfma_f32_16x16x32_bf16 v[58:61], v[142:145], v[178:181], v[58:61]
	v_mfma_f32_16x16x32_bf16 v[46:49], v[134:137], v[186:189], v[46:49]
	v_mfma_f32_16x16x32_bf16 v[42:45], v[142:145], v[186:189], v[42:45]
	v_mfma_f32_16x16x32_bf16 v[30:33], v[134:137], v[204:207], v[30:33]
	v_mfma_f32_16x16x32_bf16 v[26:29], v[142:145], v[204:207], v[26:29]
	v_mfma_f32_16x16x32_bf16 v[14:17], v[134:137], v[212:215], v[14:17]
	v_mfma_f32_16x16x32_bf16 v[10:13], v[142:145], v[212:215], v[10:13]
	v_mfma_f32_16x16x32_bf16 v[62:65], v[138:141], v[182:185], v[62:65]
	v_mfma_f32_16x16x32_bf16 v[58:61], v[146:149], v[182:185], v[58:61]
	v_mfma_f32_16x16x32_bf16 v[46:49], v[138:141], v[190:193], v[46:49]
	v_mfma_f32_16x16x32_bf16 v[42:45], v[146:149], v[190:193], v[42:45]
	v_mfma_f32_16x16x32_bf16 v[30:33], v[138:141], v[208:211], v[30:33]
	v_mfma_f32_16x16x32_bf16 v[26:29], v[146:149], v[208:211], v[26:29]
	v_mfma_f32_16x16x32_bf16 v[14:17], v[138:141], v[216:219], v[14:17]
	v_mfma_f32_16x16x32_bf16 v[10:13], v[146:149], v[216:219], v[10:13]
	s_setprio 0
	s_setprio 1
	v_mfma_f32_16x16x32_bf16 v[54:57], v[150:153], v[178:181], v[54:57]
	v_mfma_f32_16x16x32_bf16 v[50:53], v[158:161], v[178:181], v[50:53]
	v_mfma_f32_16x16x32_bf16 v[38:41], v[150:153], v[186:189], v[38:41]
	v_mfma_f32_16x16x32_bf16 v[34:37], v[158:161], v[186:189], v[34:37]
	v_mfma_f32_16x16x32_bf16 v[22:25], v[150:153], v[204:207], v[22:25]
	v_mfma_f32_16x16x32_bf16 v[18:21], v[158:161], v[204:207], v[18:21]
	v_mfma_f32_16x16x32_bf16 v[6:9], v[150:153], v[212:215], v[6:9]
	v_mfma_f32_16x16x32_bf16 v[2:5], v[158:161], v[212:215], v[2:5]
	v_mfma_f32_16x16x32_bf16 v[54:57], v[154:157], v[182:185], v[54:57]
	v_mfma_f32_16x16x32_bf16 v[50:53], v[174:177], v[182:185], v[50:53]
	v_mfma_f32_16x16x32_bf16 v[38:41], v[154:157], v[190:193], v[38:41]
	v_mfma_f32_16x16x32_bf16 v[34:37], v[174:177], v[190:193], v[34:37]
	v_mfma_f32_16x16x32_bf16 v[22:25], v[154:157], v[208:211], v[22:25]
	v_mfma_f32_16x16x32_bf16 v[18:21], v[174:177], v[208:211], v[18:21]
	v_mfma_f32_16x16x32_bf16 v[6:9], v[154:157], v[216:219], v[6:9]
	v_mfma_f32_16x16x32_bf16 v[2:5], v[174:177], v[216:219], v[2:5]
	s_setprio 0
	s_barrier
	s_add_i32 s0, 0, 0x18000
	s_add_i32 s1, 0, 0x1c000
	s_add_u32 s44, vcc_lo, 0x80000
	s_addc_u32 s45, vcc_hi, 0
	s_mov_b32 m0, s8
	v_lshl_add_u64 v[230:231], s[44:45], 0, v[164:165]
	global_load_lds_dwordx4 v[230:231], off
	v_lshl_add_u64 v[230:231], s[44:45], 0, v[162:163]
	s_mov_b32 m0, s9
	s_nop 0
	global_load_lds_dwordx4 v[230:231], off
	v_add_u32_e32 v146, s0, v1
	v_add_u32_e32 v174, s1, v1
	ds_read_b128 v[134:137], v146
	ds_read_b128 v[138:141], v146 offset:1024
	ds_read_b128 v[142:145], v146 offset:2048
	ds_read_b128 v[146:149], v146 offset:3072
	ds_read_b128 v[150:153], v174
	ds_read_b128 v[154:157], v174 offset:1024
	ds_read_b128 v[158:161], v174 offset:2048
	ds_read_b128 v[174:177], v174 offset:3072
	ds_read_b128 v[178:181], v222 offset:32768
	ds_read_b128 v[182:185], v222 offset:33792
	ds_read_b128 v[186:189], v222 offset:34816
	ds_read_b128 v[190:193], v222 offset:35840
	ds_read_b128 v[204:207], v222 offset:36864
	ds_read_b128 v[208:211], v222 offset:37888
	ds_read_b128 v[212:215], v222 offset:38912
	ds_read_b128 v[216:219], v222 offset:39936
	s_waitcnt vmcnt(8)
	s_waitcnt lgkmcnt(0)
	s_barrier
	s_setprio 1
	s_waitcnt lgkmcnt(0)
	v_mfma_f32_16x16x32_bf16 v[126:129], v[134:137], v[178:181], v[126:129]
	v_mfma_f32_16x16x32_bf16 v[122:125], v[142:145], v[178:181], v[122:125]
	v_mfma_f32_16x16x32_bf16 v[110:113], v[134:137], v[186:189], v[110:113]
	v_mfma_f32_16x16x32_bf16 v[106:109], v[142:145], v[186:189], v[106:109]
	v_mfma_f32_16x16x32_bf16 v[94:97], v[134:137], v[204:207], v[94:97]
	v_mfma_f32_16x16x32_bf16 v[90:93], v[142:145], v[204:207], v[90:93]
	v_mfma_f32_16x16x32_bf16 v[78:81], v[134:137], v[212:215], v[78:81]
	v_mfma_f32_16x16x32_bf16 v[74:77], v[142:145], v[212:215], v[74:77]
	v_mfma_f32_16x16x32_bf16 v[126:129], v[138:141], v[182:185], v[126:129]
	v_mfma_f32_16x16x32_bf16 v[122:125], v[146:149], v[182:185], v[122:125]
	v_mfma_f32_16x16x32_bf16 v[110:113], v[138:141], v[190:193], v[110:113]
	v_mfma_f32_16x16x32_bf16 v[106:109], v[146:149], v[190:193], v[106:109]
	v_mfma_f32_16x16x32_bf16 v[94:97], v[138:141], v[208:211], v[94:97]
	v_mfma_f32_16x16x32_bf16 v[90:93], v[146:149], v[208:211], v[90:93]
	v_mfma_f32_16x16x32_bf16 v[78:81], v[138:141], v[216:219], v[78:81]
	v_mfma_f32_16x16x32_bf16 v[74:77], v[146:149], v[216:219], v[74:77]
	s_setprio 0
	s_setprio 1
	v_mfma_f32_16x16x32_bf16 v[118:121], v[150:153], v[178:181], v[118:121]
	v_mfma_f32_16x16x32_bf16 v[114:117], v[158:161], v[178:181], v[114:117]
	v_mfma_f32_16x16x32_bf16 v[102:105], v[150:153], v[186:189], v[102:105]
	v_mfma_f32_16x16x32_bf16 v[98:101], v[158:161], v[186:189], v[98:101]
	v_mfma_f32_16x16x32_bf16 v[86:89], v[150:153], v[204:207], v[86:89]
	v_mfma_f32_16x16x32_bf16 v[82:85], v[158:161], v[204:207], v[82:85]
	v_mfma_f32_16x16x32_bf16 v[70:73], v[150:153], v[212:215], v[70:73]
	v_mfma_f32_16x16x32_bf16 v[66:69], v[158:161], v[212:215], v[66:69]
	v_mfma_f32_16x16x32_bf16 v[118:121], v[154:157], v[182:185], v[118:121]
	v_mfma_f32_16x16x32_bf16 v[114:117], v[174:177], v[182:185], v[114:117]
	v_mfma_f32_16x16x32_bf16 v[102:105], v[154:157], v[190:193], v[102:105]
	v_mfma_f32_16x16x32_bf16 v[98:101], v[174:177], v[190:193], v[98:101]
	v_mfma_f32_16x16x32_bf16 v[86:89], v[154:157], v[208:211], v[86:89]
	v_mfma_f32_16x16x32_bf16 v[82:85], v[174:177], v[208:211], v[82:85]
	v_mfma_f32_16x16x32_bf16 v[70:73], v[154:157], v[216:219], v[70:73]
	v_mfma_f32_16x16x32_bf16 v[66:69], v[174:177], v[216:219], v[66:69]
	s_setprio 0
	s_barrier
	s_add_i32 s0, s0, s54
	v_lshl_add_u64 v[220:221], v[220:221], 0, s[82:83]
	s_mov_b32 m0, s0
	s_nop 0
	global_load_lds_dwordx4 v[220:221], off
	s_add_i32 m0, s0, 0x2000
	s_add_u32 s44, s70, 0x80080
	v_lshl_add_u64 v[220:221], v[224:225], 0, s[82:83]
	s_addc_u32 s45, s71, 0
	s_add_i32 s0, s1, s54
	global_load_lds_dwordx4 v[220:221], off
	v_lshl_add_u64 v[220:221], s[44:45], 0, v[164:165]
	s_mov_b32 m0, s0
	s_nop 0
	global_load_lds_dwordx4 v[220:221], off
	v_lshl_add_u64 v[220:221], s[44:45], 0, v[162:163]
	s_add_i32 m0, s0, 0x2000
	s_nop 0
	global_load_lds_dwordx4 v[220:221], off
	v_lshl_add_u64 v[220:221], v[226:227], 0, s[82:83]
	s_mov_b32 m0, s27
	s_nop 0
	global_load_lds_dwordx4 v[220:221], off
	v_lshl_add_u64 v[220:221], v[228:229], 0, s[82:83]
	s_mov_b32 m0, s26
	s_nop 0
	global_load_lds_dwordx4 v[220:221], off
	ds_read_b128 v[178:181], v222 offset:49152
	ds_read_b128 v[182:185], v222 offset:50176
	ds_read_b128 v[186:189], v222 offset:51200
	ds_read_b128 v[190:193], v222 offset:52224
	ds_read_b128 v[204:207], v222 offset:53248
	ds_read_b128 v[208:211], v222 offset:54272
	ds_read_b128 v[212:215], v222 offset:55296
	ds_read_b128 v[216:219], v222 offset:56320
	s_waitcnt vmcnt(8)
	s_waitcnt lgkmcnt(0)
	s_barrier
	s_setprio 1
	s_waitcnt lgkmcnt(0)
	v_mfma_f32_16x16x32_bf16 v[62:65], v[134:137], v[178:181], v[62:65]
	v_mfma_f32_16x16x32_bf16 v[58:61], v[142:145], v[178:181], v[58:61]
	v_mfma_f32_16x16x32_bf16 v[46:49], v[134:137], v[186:189], v[46:49]
	v_mfma_f32_16x16x32_bf16 v[42:45], v[142:145], v[186:189], v[42:45]
	v_mfma_f32_16x16x32_bf16 v[30:33], v[134:137], v[204:207], v[30:33]
	v_mfma_f32_16x16x32_bf16 v[26:29], v[142:145], v[204:207], v[26:29]
	v_mfma_f32_16x16x32_bf16 v[14:17], v[134:137], v[212:215], v[14:17]
	v_mfma_f32_16x16x32_bf16 v[10:13], v[142:145], v[212:215], v[10:13]
	v_mfma_f32_16x16x32_bf16 v[62:65], v[138:141], v[182:185], v[62:65]
	v_mfma_f32_16x16x32_bf16 v[58:61], v[146:149], v[182:185], v[58:61]
	v_mfma_f32_16x16x32_bf16 v[46:49], v[138:141], v[190:193], v[46:49]
	v_mfma_f32_16x16x32_bf16 v[42:45], v[146:149], v[190:193], v[42:45]
	v_mfma_f32_16x16x32_bf16 v[30:33], v[138:141], v[208:211], v[30:33]
	v_mfma_f32_16x16x32_bf16 v[26:29], v[146:149], v[208:211], v[26:29]
	v_mfma_f32_16x16x32_bf16 v[14:17], v[138:141], v[216:219], v[14:17]
	v_mfma_f32_16x16x32_bf16 v[10:13], v[146:149], v[216:219], v[10:13]
	s_setprio 0
	s_setprio 1
	v_mfma_f32_16x16x32_bf16 v[54:57], v[150:153], v[178:181], v[54:57]
	v_mfma_f32_16x16x32_bf16 v[50:53], v[158:161], v[178:181], v[50:53]
	v_mfma_f32_16x16x32_bf16 v[38:41], v[150:153], v[186:189], v[38:41]
	v_mfma_f32_16x16x32_bf16 v[34:37], v[158:161], v[186:189], v[34:37]
	v_mfma_f32_16x16x32_bf16 v[22:25], v[150:153], v[204:207], v[22:25]
	v_mfma_f32_16x16x32_bf16 v[18:21], v[158:161], v[204:207], v[18:21]
	v_mfma_f32_16x16x32_bf16 v[6:9], v[150:153], v[212:215], v[6:9]
	v_mfma_f32_16x16x32_bf16 v[2:5], v[158:161], v[212:215], v[2:5]
	v_mfma_f32_16x16x32_bf16 v[54:57], v[154:157], v[182:185], v[54:57]
	v_mfma_f32_16x16x32_bf16 v[50:53], v[174:177], v[182:185], v[50:53]
	v_mfma_f32_16x16x32_bf16 v[38:41], v[154:157], v[190:193], v[38:41]
	v_mfma_f32_16x16x32_bf16 v[34:37], v[174:177], v[190:193], v[34:37]
	v_mfma_f32_16x16x32_bf16 v[22:25], v[154:157], v[208:211], v[22:25]
	v_mfma_f32_16x16x32_bf16 v[18:21], v[174:177], v[208:211], v[18:21]
	v_mfma_f32_16x16x32_bf16 v[6:9], v[154:157], v[216:219], v[6:9]
	v_mfma_f32_16x16x32_bf16 v[2:5], v[174:177], v[216:219], v[2:5]
	s_setprio 0
	s_barrier
	s_add_i32 s43, s43, 2
	s_add_u32 s76, s76, 0x100
	s_addc_u32 s77, s77, 0
	s_add_u32 s7, s7, 0x100
	s_addc_u32 s41, s41, 0
	s_cmp_gt_u32 s43, 29
	s_cbranch_scc1 .LBB0_288

.LBB0_509:
	s_add_u32 s90, s76, 0x100
	s_addc_u32 s91, s77, 0
	s_and_b64 s[0:1], s[70:71], exec
	s_cselect_b32 vcc_hi, s22, s91
	s_cselect_b32 vcc_lo, s23, s90
	s_cselect_b32 s71, s41, s53
	s_cselect_b32 s70, s44, s51
	s_add_i32 s0, 0, 0x10000
	s_add_i32 s18, 0, 0x14000
	v_lshl_add_u64 v[218:219], s[76:77], 0, v[210:211]
	s_add_i32 m0, s29, 0xc000
	s_nop 0
	global_load_lds_dwordx4 v[218:219], off
	v_lshl_add_u64 v[218:219], s[76:77], 0, v[212:213]
	s_add_i32 m0, s29, 0xe000
	s_nop 0
	global_load_lds_dwordx4 v[218:219], off
	v_add_u32_e32 v114, s0, v1
	v_add_u32_e32 v154, s18, v1
	ds_read_b128 v[78:81], v114
	ds_read_b128 v[90:93], v114 offset:1024
	ds_read_b128 v[102:105], v114 offset:2048
	ds_read_b128 v[114:117], v114 offset:3072
	ds_read_b128 v[126:129], v154
	ds_read_b128 v[134:137], v154 offset:1024
	ds_read_b128 v[142:145], v154 offset:2048
	ds_read_b128 v[154:157], v154 offset:3072
	ds_read_b128 v[158:161], v237
	ds_read_b128 v[162:165], v237 offset:1024
	ds_read_b128 v[166:169], v237 offset:2048
	ds_read_b128 v[178:181], v237 offset:3072
	ds_read_b128 v[182:185], v237 offset:4096
	ds_read_b128 v[186:189], v237 offset:5120
	ds_read_b128 v[190:193], v237 offset:6144
	ds_read_b128 v[214:217], v237 offset:7168
	s_waitcnt vmcnt(8)
	s_waitcnt lgkmcnt(0)
	s_barrier
	s_setprio 1
	s_waitcnt lgkmcnt(0)
	v_mfma_f32_16x16x32_bf16 v[174:177], v[78:81], v[158:161], v[174:177]
	v_mfma_f32_16x16x32_bf16 v[170:173], v[102:105], v[158:161], v[170:173]
	v_mfma_f32_16x16x32_bf16 v[138:141], v[78:81], v[166:169], v[138:141]
	v_mfma_f32_16x16x32_bf16 v[130:133], v[102:105], v[166:169], v[130:133]
	v_mfma_f32_16x16x32_bf16 v[110:113], v[78:81], v[182:185], v[110:113]
	v_mfma_f32_16x16x32_bf16 v[106:109], v[102:105], v[182:185], v[106:109]
	v_mfma_f32_16x16x32_bf16 v[86:89], v[78:81], v[190:193], v[86:89]
	v_mfma_f32_16x16x32_bf16 v[82:85], v[102:105], v[190:193], v[82:85]
	v_mfma_f32_16x16x32_bf16 v[174:177], v[90:93], v[162:165], v[174:177]
	v_mfma_f32_16x16x32_bf16 v[170:173], v[114:117], v[162:165], v[170:173]
	v_mfma_f32_16x16x32_bf16 v[138:141], v[90:93], v[178:181], v[138:141]
	v_mfma_f32_16x16x32_bf16 v[130:133], v[114:117], v[178:181], v[130:133]
	v_mfma_f32_16x16x32_bf16 v[110:113], v[90:93], v[186:189], v[110:113]
	v_mfma_f32_16x16x32_bf16 v[106:109], v[114:117], v[186:189], v[106:109]
	v_mfma_f32_16x16x32_bf16 v[86:89], v[90:93], v[214:217], v[86:89]
	v_mfma_f32_16x16x32_bf16 v[82:85], v[114:117], v[214:217], v[82:85]
	s_setprio 0
	s_setprio 1
	v_mfma_f32_16x16x32_bf16 v[150:153], v[126:129], v[158:161], v[150:153]
	v_mfma_f32_16x16x32_bf16 v[146:149], v[142:145], v[158:161], v[146:149]
	v_mfma_f32_16x16x32_bf16 v[122:125], v[126:129], v[166:169], v[122:125]
	v_mfma_f32_16x16x32_bf16 v[118:121], v[142:145], v[166:169], v[118:121]
	v_mfma_f32_16x16x32_bf16 v[98:101], v[126:129], v[182:185], v[98:101]
	v_mfma_f32_16x16x32_bf16 v[94:97], v[142:145], v[182:185], v[94:97]
	v_mfma_f32_16x16x32_bf16 v[74:77], v[126:129], v[190:193], v[74:77]
	v_mfma_f32_16x16x32_bf16 v[66:69], v[142:145], v[190:193], v[66:69]
	v_mfma_f32_16x16x32_bf16 v[150:153], v[134:137], v[162:165], v[150:153]
	v_mfma_f32_16x16x32_bf16 v[146:149], v[154:157], v[162:165], v[146:149]
	v_mfma_f32_16x16x32_bf16 v[122:125], v[134:137], v[178:181], v[122:125]
	v_mfma_f32_16x16x32_bf16 v[118:121], v[154:157], v[178:181], v[118:121]
	v_mfma_f32_16x16x32_bf16 v[98:101], v[134:137], v[186:189], v[98:101]
	v_mfma_f32_16x16x32_bf16 v[94:97], v[154:157], v[186:189], v[94:97]
	v_mfma_f32_16x16x32_bf16 v[74:77], v[134:137], v[214:217], v[74:77]
	v_mfma_f32_16x16x32_bf16 v[66:69], v[154:157], v[214:217], v[66:69]
	s_setprio 0
	s_barrier
	s_add_i32 s0, s0, s28
	v_lshl_add_u64 v[218:219], s[70:71], 0, v[194:195]
	s_mov_b32 m0, s0
	s_nop 0
	global_load_lds_dwordx4 v[218:219], off
	s_add_i32 m0, s0, 0x2000
	s_add_u32 s0, s70, 0x80000
	v_lshl_add_u64 v[220:221], s[70:71], 0, v[204:205]
	s_addc_u32 s1, s71, 0
	s_add_i32 s18, s18, s28
	global_load_lds_dwordx4 v[220:221], off
	v_lshl_add_u64 v[222:223], s[0:1], 0, v[194:195]
	s_mov_b32 m0, s18
	v_lshl_add_u64 v[224:225], vcc, 0, v[204:205]
	global_load_lds_dwordx4 v[222:223], off
	v_lshl_add_u64 v[222:223], s[0:1], 0, v[204:205]
	s_add_i32 m0, s18, 0x2000
	s_nop 0
	global_load_lds_dwordx4 v[222:223], off
	v_lshl_add_u64 v[222:223], vcc, 0, v[194:195]
	s_mov_b32 m0, s29
	s_nop 0
	global_load_lds_dwordx4 v[222:223], off
	s_mov_b32 m0, s31
	s_nop 0
	global_load_lds_dwordx4 v[224:225], off
	ds_read_b128 v[158:161], v237 offset:16384
	ds_read_b128 v[162:165], v237 offset:17408
	ds_read_b128 v[166:169], v237 offset:18432
	ds_read_b128 v[178:181], v237 offset:19456
	ds_read_b128 v[182:185], v237 offset:20480
	ds_read_b128 v[186:189], v237 offset:21504
	ds_read_b128 v[190:193], v237 offset:22528
	ds_read_b128 v[214:217], v237 offset:23552
	s_waitcnt vmcnt(8)
	s_waitcnt lgkmcnt(0)
	s_barrier
	s_setprio 1
	s_waitcnt lgkmcnt(0)
	v_mfma_f32_16x16x32_bf16 v[62:65], v[78:81], v[158:161], v[62:65]
	v_mfma_f32_16x16x32_bf16 v[58:61], v[102:105], v[158:161], v[58:61]
	v_mfma_f32_16x16x32_bf16 v[46:49], v[78:81], v[166:169], v[46:49]
	v_mfma_f32_16x16x32_bf16 v[42:45], v[102:105], v[166:169], v[42:45]
	v_mfma_f32_16x16x32_bf16 v[30:33], v[78:81], v[182:185], v[30:33]
	v_mfma_f32_16x16x32_bf16 v[26:29], v[102:105], v[182:185], v[26:29]
	v_mfma_f32_16x16x32_bf16 v[14:17], v[78:81], v[190:193], v[14:17]
	v_mfma_f32_16x16x32_bf16 v[10:13], v[102:105], v[190:193], v[10:13]
	v_mfma_f32_16x16x32_bf16 v[62:65], v[90:93], v[162:165], v[62:65]
	v_mfma_f32_16x16x32_bf16 v[58:61], v[114:117], v[162:165], v[58:61]
	v_mfma_f32_16x16x32_bf16 v[46:49], v[90:93], v[178:181], v[46:49]
	v_mfma_f32_16x16x32_bf16 v[42:45], v[114:117], v[178:181], v[42:45]
	v_mfma_f32_16x16x32_bf16 v[30:33], v[90:93], v[186:189], v[30:33]
	v_mfma_f32_16x16x32_bf16 v[26:29], v[114:117], v[186:189], v[26:29]
	v_mfma_f32_16x16x32_bf16 v[14:17], v[90:93], v[214:217], v[14:17]
	v_mfma_f32_16x16x32_bf16 v[10:13], v[114:117], v[214:217], v[10:13]
	s_setprio 0
	s_setprio 1
	v_mfma_f32_16x16x32_bf16 v[54:57], v[126:129], v[158:161], v[54:57]
	v_mfma_f32_16x16x32_bf16 v[50:53], v[142:145], v[158:161], v[50:53]
	v_mfma_f32_16x16x32_bf16 v[38:41], v[126:129], v[166:169], v[38:41]
	v_mfma_f32_16x16x32_bf16 v[34:37], v[142:145], v[166:169], v[34:37]
	v_mfma_f32_16x16x32_bf16 v[22:25], v[126:129], v[182:185], v[22:25]
	v_mfma_f32_16x16x32_bf16 v[18:21], v[142:145], v[182:185], v[18:21]
	v_mfma_f32_16x16x32_bf16 v[6:9], v[126:129], v[190:193], v[6:9]
	v_mfma_f32_16x16x32_bf16 v[2:5], v[142:145], v[190:193], v[2:5]
	v_mfma_f32_16x16x32_bf16 v[54:57], v[134:137], v[162:165], v[54:57]
	v_mfma_f32_16x16x32_bf16 v[50:53], v[154:157], v[162:165], v[50:53]
	v_mfma_f32_16x16x32_bf16 v[38:41], v[134:137], v[178:181], v[38:41]
	v_mfma_f32_16x16x32_bf16 v[34:37], v[154:157], v[178:181], v[34:37]
	v_mfma_f32_16x16x32_bf16 v[22:25], v[134:137], v[186:189], v[22:25]
	v_mfma_f32_16x16x32_bf16 v[18:21], v[154:157], v[186:189], v[18:21]
	v_mfma_f32_16x16x32_bf16 v[6:9], v[134:137], v[214:217], v[6:9]
	v_mfma_f32_16x16x32_bf16 v[2:5], v[154:157], v[214:217], v[2:5]
	s_setprio 0
	s_barrier
	s_add_i32 s18, 0, 0x18000
	s_add_i32 s19, 0, 0x1c000
	s_add_u32 s0, vcc_lo, 0x80000
	s_addc_u32 s1, vcc_hi, 0
	s_mov_b32 m0, s33
	v_lshl_add_u64 v[226:227], s[0:1], 0, v[194:195]
	global_load_lds_dwordx4 v[226:227], off
	v_lshl_add_u64 v[226:227], s[0:1], 0, v[204:205]
	s_mov_b32 m0, s43
	s_nop 0
	global_load_lds_dwordx4 v[226:227], off
	v_add_u32_e32 v114, s18, v1
	v_add_u32_e32 v154, s19, v1
	ds_read_b128 v[78:81], v114
	ds_read_b128 v[90:93], v114 offset:1024
	ds_read_b128 v[102:105], v114 offset:2048
	ds_read_b128 v[114:117], v114 offset:3072
	ds_read_b128 v[126:129], v154
	ds_read_b128 v[134:137], v154 offset:1024
	ds_read_b128 v[142:145], v154 offset:2048
	ds_read_b128 v[154:157], v154 offset:3072
	ds_read_b128 v[158:161], v237 offset:32768
	ds_read_b128 v[162:165], v237 offset:33792
	ds_read_b128 v[166:169], v237 offset:34816
	ds_read_b128 v[178:181], v237 offset:35840
	ds_read_b128 v[182:185], v237 offset:36864
	ds_read_b128 v[186:189], v237 offset:37888
	ds_read_b128 v[190:193], v237 offset:38912
	ds_read_b128 v[214:217], v237 offset:39936
	s_waitcnt vmcnt(8)
	s_waitcnt lgkmcnt(0)
	s_barrier
	s_setprio 1
	s_waitcnt lgkmcnt(0)
	v_mfma_f32_16x16x32_bf16 v[174:177], v[78:81], v[158:161], v[174:177]
	v_mfma_f32_16x16x32_bf16 v[170:173], v[102:105], v[158:161], v[170:173]
	v_mfma_f32_16x16x32_bf16 v[138:141], v[78:81], v[166:169], v[138:141]
	v_mfma_f32_16x16x32_bf16 v[130:133], v[102:105], v[166:169], v[130:133]
	v_mfma_f32_16x16x32_bf16 v[110:113], v[78:81], v[182:185], v[110:113]
	v_mfma_f32_16x16x32_bf16 v[106:109], v[102:105], v[182:185], v[106:109]
	v_mfma_f32_16x16x32_bf16 v[86:89], v[78:81], v[190:193], v[86:89]
	v_mfma_f32_16x16x32_bf16 v[82:85], v[102:105], v[190:193], v[82:85]
	v_mfma_f32_16x16x32_bf16 v[174:177], v[90:93], v[162:165], v[174:177]
	v_mfma_f32_16x16x32_bf16 v[170:173], v[114:117], v[162:165], v[170:173]
	v_mfma_f32_16x16x32_bf16 v[138:141], v[90:93], v[178:181], v[138:141]
	v_mfma_f32_16x16x32_bf16 v[130:133], v[114:117], v[178:181], v[130:133]
	v_mfma_f32_16x16x32_bf16 v[110:113], v[90:93], v[186:189], v[110:113]
	v_mfma_f32_16x16x32_bf16 v[106:109], v[114:117], v[186:189], v[106:109]
	v_mfma_f32_16x16x32_bf16 v[86:89], v[90:93], v[214:217], v[86:89]
	v_mfma_f32_16x16x32_bf16 v[82:85], v[114:117], v[214:217], v[82:85]
	s_setprio 0
	s_setprio 1
	v_mfma_f32_16x16x32_bf16 v[150:153], v[126:129], v[158:161], v[150:153]
	v_mfma_f32_16x16x32_bf16 v[146:149], v[142:145], v[158:161], v[146:149]
	v_mfma_f32_16x16x32_bf16 v[122:125], v[126:129], v[166:169], v[122:125]
	v_mfma_f32_16x16x32_bf16 v[118:121], v[142:145], v[166:169], v[118:121]
	v_mfma_f32_16x16x32_bf16 v[98:101], v[126:129], v[182:185], v[98:101]
	v_mfma_f32_16x16x32_bf16 v[94:97], v[142:145], v[182:185], v[94:97]
	v_mfma_f32_16x16x32_bf16 v[74:77], v[126:129], v[190:193], v[74:77]
	v_mfma_f32_16x16x32_bf16 v[66:69], v[142:145], v[190:193], v[66:69]
	v_mfma_f32_16x16x32_bf16 v[150:153], v[134:137], v[162:165], v[150:153]
	v_mfma_f32_16x16x32_bf16 v[146:149], v[154:157], v[162:165], v[146:149]
	v_mfma_f32_16x16x32_bf16 v[122:125], v[134:137], v[178:181], v[122:125]
	v_mfma_f32_16x16x32_bf16 v[118:121], v[154:157], v[178:181], v[118:121]
	v_mfma_f32_16x16x32_bf16 v[98:101], v[134:137], v[186:189], v[98:101]
	v_mfma_f32_16x16x32_bf16 v[94:97], v[154:157], v[186:189], v[94:97]
	v_mfma_f32_16x16x32_bf16 v[74:77], v[134:137], v[214:217], v[74:77]
	v_mfma_f32_16x16x32_bf16 v[66:69], v[154:157], v[214:217], v[66:69]
	s_setprio 0
	s_barrier
	s_add_i32 s0, s18, s28
	v_lshl_add_u64 v[218:219], v[218:219], 0, s[82:83]
	s_mov_b32 m0, s0
	s_nop 0
	global_load_lds_dwordx4 v[218:219], off
	s_add_i32 m0, s0, 0x2000
	s_add_u32 s0, s70, 0x80080
	v_lshl_add_u64 v[218:219], v[220:221], 0, s[82:83]
	s_addc_u32 s1, s71, 0
	s_add_i32 s18, s19, s28
	global_load_lds_dwordx4 v[218:219], off
	v_lshl_add_u64 v[218:219], s[0:1], 0, v[194:195]
	s_mov_b32 m0, s18
	s_nop 0
	global_load_lds_dwordx4 v[218:219], off
	v_lshl_add_u64 v[218:219], s[0:1], 0, v[204:205]
	s_add_i32 m0, s18, 0x2000
	s_nop 0
	global_load_lds_dwordx4 v[218:219], off
	v_lshl_add_u64 v[218:219], v[222:223], 0, s[82:83]
	s_mov_b32 m0, s68
	s_nop 0
	global_load_lds_dwordx4 v[218:219], off
	v_lshl_add_u64 v[218:219], v[224:225], 0, s[82:83]
	s_mov_b32 m0, s79
	s_nop 0
	global_load_lds_dwordx4 v[218:219], off
	ds_read_b128 v[158:161], v237 offset:49152
	ds_read_b128 v[162:165], v237 offset:50176
	ds_read_b128 v[166:169], v237 offset:51200
	ds_read_b128 v[178:181], v237 offset:52224
	ds_read_b128 v[182:185], v237 offset:53248
	ds_read_b128 v[186:189], v237 offset:54272
	ds_read_b128 v[190:193], v237 offset:55296
	ds_read_b128 v[214:217], v237 offset:56320
	s_waitcnt vmcnt(8)
	s_waitcnt lgkmcnt(0)
	s_barrier
	s_setprio 1
	s_waitcnt lgkmcnt(0)
	v_mfma_f32_16x16x32_bf16 v[62:65], v[78:81], v[158:161], v[62:65]
	v_mfma_f32_16x16x32_bf16 v[58:61], v[102:105], v[158:161], v[58:61]
	v_mfma_f32_16x16x32_bf16 v[46:49], v[78:81], v[166:169], v[46:49]
	v_mfma_f32_16x16x32_bf16 v[42:45], v[102:105], v[166:169], v[42:45]
	v_mfma_f32_16x16x32_bf16 v[30:33], v[78:81], v[182:185], v[30:33]
	v_mfma_f32_16x16x32_bf16 v[26:29], v[102:105], v[182:185], v[26:29]
	v_mfma_f32_16x16x32_bf16 v[14:17], v[78:81], v[190:193], v[14:17]
	v_mfma_f32_16x16x32_bf16 v[10:13], v[102:105], v[190:193], v[10:13]
	v_mfma_f32_16x16x32_bf16 v[62:65], v[90:93], v[162:165], v[62:65]
	v_mfma_f32_16x16x32_bf16 v[58:61], v[114:117], v[162:165], v[58:61]
	v_mfma_f32_16x16x32_bf16 v[46:49], v[90:93], v[178:181], v[46:49]
	v_mfma_f32_16x16x32_bf16 v[42:45], v[114:117], v[178:181], v[42:45]
	v_mfma_f32_16x16x32_bf16 v[30:33], v[90:93], v[186:189], v[30:33]
	v_mfma_f32_16x16x32_bf16 v[26:29], v[114:117], v[186:189], v[26:29]
	v_mfma_f32_16x16x32_bf16 v[14:17], v[90:93], v[214:217], v[14:17]
	v_mfma_f32_16x16x32_bf16 v[10:13], v[114:117], v[214:217], v[10:13]
	s_setprio 0
	s_setprio 1
	v_mfma_f32_16x16x32_bf16 v[54:57], v[126:129], v[158:161], v[54:57]
	v_mfma_f32_16x16x32_bf16 v[50:53], v[142:145], v[158:161], v[50:53]
	v_mfma_f32_16x16x32_bf16 v[38:41], v[126:129], v[166:169], v[38:41]
	v_mfma_f32_16x16x32_bf16 v[34:37], v[142:145], v[166:169], v[34:37]
	v_mfma_f32_16x16x32_bf16 v[22:25], v[126:129], v[182:185], v[22:25]
	v_mfma_f32_16x16x32_bf16 v[18:21], v[142:145], v[182:185], v[18:21]
	v_mfma_f32_16x16x32_bf16 v[6:9], v[126:129], v[190:193], v[6:9]
	v_mfma_f32_16x16x32_bf16 v[2:5], v[142:145], v[190:193], v[2:5]
	v_mfma_f32_16x16x32_bf16 v[54:57], v[134:137], v[162:165], v[54:57]
	v_mfma_f32_16x16x32_bf16 v[50:53], v[154:157], v[162:165], v[50:53]
	v_mfma_f32_16x16x32_bf16 v[38:41], v[134:137], v[178:181], v[38:41]
	v_mfma_f32_16x16x32_bf16 v[34:37], v[154:157], v[178:181], v[34:37]
	v_mfma_f32_16x16x32_bf16 v[22:25], v[134:137], v[186:189], v[22:25]
	v_mfma_f32_16x16x32_bf16 v[18:21], v[154:157], v[186:189], v[18:21]
	v_mfma_f32_16x16x32_bf16 v[6:9], v[134:137], v[214:217], v[6:9]
	v_mfma_f32_16x16x32_bf16 v[2:5], v[154:157], v[214:217], v[2:5]
	s_setprio 0
	s_barrier
	s_add_i32 s57, s57, 2
	s_add_u32 s51, s51, 0x100
	s_addc_u32 s53, s53, 0
	s_cmp_gt_u32 s57, 29
	s_mov_b64 s[76:77], s[90:91]
	s_cbranch_scc1 .LBB0_512

.LBB0_581:
	s_add_u32 s18, s62, 0xfff80080
	s_addc_u32 s19, s63, -1
	s_and_b64 s[0:1], s[64:65], exec
	s_cselect_b32 s71, s22, s19
	s_cselect_b32 s70, s23, s18
	s_cselect_b32 s65, s39, s58
	s_cselect_b32 s64, s47, s53
	s_add_i32 s0, 0, 0x10000
	s_add_i32 s18, 0, 0x14000
	v_lshl_add_u64 v[220:221], s[62:63], 0, v[136:137]
	s_add_i32 m0, s29, 0xc000
	s_nop 0
	global_load_lds_dwordx4 v[220:221], off
	v_lshl_add_u64 v[220:221], s[62:63], 0, v[138:139]
	s_add_i32 m0, s29, 0xe000
	s_nop 0
	global_load_lds_dwordx4 v[220:221], off
	v_add_u32_e32 v153, s0, v1
	ds_read_b128 v[144:147], v153
	ds_read_b128 v[148:151], v153 offset:1024
	ds_read_b128 v[154:157], v153 offset:2048
	ds_read_b128 v[158:161], v153 offset:3072
	v_add_u32_e32 v153, s18, v1
	ds_read_b128 v[162:165], v153
	ds_read_b128 v[166:169], v153 offset:1024
	ds_read_b128 v[170:173], v153 offset:2048
	ds_read_b128 v[174:177], v153 offset:3072
	ds_read_b128 v[178:181], v152
	ds_read_b128 v[182:185], v152 offset:1024
	ds_read_b128 v[186:189], v152 offset:2048
	ds_read_b128 v[190:193], v152 offset:3072
	ds_read_b128 v[204:207], v152 offset:4096
	ds_read_b128 v[208:211], v152 offset:5120
	ds_read_b128 v[212:215], v152 offset:6144
	ds_read_b128 v[216:219], v152 offset:7168
	s_waitcnt vmcnt(8)
	s_waitcnt lgkmcnt(0)
	s_barrier
	s_setprio 1
	s_waitcnt lgkmcnt(0)
	v_mfma_f32_16x16x32_bf16 v[126:129], v[144:147], v[178:181], v[126:129]
	v_mfma_f32_16x16x32_bf16 v[122:125], v[154:157], v[178:181], v[122:125]
	v_mfma_f32_16x16x32_bf16 v[110:113], v[144:147], v[186:189], v[110:113]
	v_mfma_f32_16x16x32_bf16 v[106:109], v[154:157], v[186:189], v[106:109]
	v_mfma_f32_16x16x32_bf16 v[94:97], v[144:147], v[204:207], v[94:97]
	v_mfma_f32_16x16x32_bf16 v[90:93], v[154:157], v[204:207], v[90:93]
	v_mfma_f32_16x16x32_bf16 v[78:81], v[144:147], v[212:215], v[78:81]
	v_mfma_f32_16x16x32_bf16 v[74:77], v[154:157], v[212:215], v[74:77]
	v_mfma_f32_16x16x32_bf16 v[126:129], v[148:151], v[182:185], v[126:129]
	v_mfma_f32_16x16x32_bf16 v[122:125], v[158:161], v[182:185], v[122:125]
	v_mfma_f32_16x16x32_bf16 v[110:113], v[148:151], v[190:193], v[110:113]
	v_mfma_f32_16x16x32_bf16 v[106:109], v[158:161], v[190:193], v[106:109]
	v_mfma_f32_16x16x32_bf16 v[94:97], v[148:151], v[208:211], v[94:97]
	v_mfma_f32_16x16x32_bf16 v[90:93], v[158:161], v[208:211], v[90:93]
	v_mfma_f32_16x16x32_bf16 v[78:81], v[148:151], v[216:219], v[78:81]
	v_mfma_f32_16x16x32_bf16 v[74:77], v[158:161], v[216:219], v[74:77]
	s_setprio 0
	s_setprio 1
	v_mfma_f32_16x16x32_bf16 v[118:121], v[162:165], v[178:181], v[118:121]
	v_mfma_f32_16x16x32_bf16 v[114:117], v[170:173], v[178:181], v[114:117]
	v_mfma_f32_16x16x32_bf16 v[102:105], v[162:165], v[186:189], v[102:105]
	v_mfma_f32_16x16x32_bf16 v[98:101], v[170:173], v[186:189], v[98:101]
	v_mfma_f32_16x16x32_bf16 v[86:89], v[162:165], v[204:207], v[86:89]
	v_mfma_f32_16x16x32_bf16 v[82:85], v[170:173], v[204:207], v[82:85]
	v_mfma_f32_16x16x32_bf16 v[70:73], v[162:165], v[212:215], v[70:73]
	v_mfma_f32_16x16x32_bf16 v[66:69], v[170:173], v[212:215], v[66:69]
	v_mfma_f32_16x16x32_bf16 v[118:121], v[166:169], v[182:185], v[118:121]
	v_mfma_f32_16x16x32_bf16 v[114:117], v[174:177], v[182:185], v[114:117]
	v_mfma_f32_16x16x32_bf16 v[102:105], v[166:169], v[190:193], v[102:105]
	v_mfma_f32_16x16x32_bf16 v[98:101], v[174:177], v[190:193], v[98:101]
	v_mfma_f32_16x16x32_bf16 v[86:89], v[166:169], v[208:211], v[86:89]
	v_mfma_f32_16x16x32_bf16 v[82:85], v[174:177], v[208:211], v[82:85]
	v_mfma_f32_16x16x32_bf16 v[70:73], v[166:169], v[216:219], v[70:73]
	v_mfma_f32_16x16x32_bf16 v[66:69], v[174:177], v[216:219], v[66:69]
	s_setprio 0
	s_barrier
	s_add_i32 s0, s0, s28
	v_lshl_add_u64 v[220:221], s[64:65], 0, v[194:195]
	s_mov_b32 m0, s0
	s_nop 0
	global_load_lds_dwordx4 v[220:221], off
	s_add_i32 m0, s0, 0x2000
	s_add_u32 s0, s64, 0x80000
	v_lshl_add_u64 v[222:223], s[64:65], 0, v[130:131]
	s_addc_u32 s1, s65, 0
	s_add_i32 s18, s18, s28
	global_load_lds_dwordx4 v[222:223], off
	v_lshl_add_u64 v[224:225], s[0:1], 0, v[194:195]
	s_mov_b32 m0, s18
	v_lshl_add_u64 v[226:227], s[70:71], 0, v[130:131]
	global_load_lds_dwordx4 v[224:225], off
	v_lshl_add_u64 v[224:225], s[0:1], 0, v[130:131]
	s_add_i32 m0, s18, 0x2000
	s_nop 0
	global_load_lds_dwordx4 v[224:225], off
	v_lshl_add_u64 v[224:225], s[70:71], 0, v[194:195]
	s_mov_b32 m0, s29
	s_nop 0
	global_load_lds_dwordx4 v[224:225], off
	s_mov_b32 m0, s31
	s_nop 0
	global_load_lds_dwordx4 v[226:227], off
	ds_read_b128 v[178:181], v152 offset:16384
	ds_read_b128 v[182:185], v152 offset:17408
	ds_read_b128 v[186:189], v152 offset:18432
	ds_read_b128 v[190:193], v152 offset:19456
	ds_read_b128 v[204:207], v152 offset:20480
	ds_read_b128 v[208:211], v152 offset:21504
	ds_read_b128 v[212:215], v152 offset:22528
	ds_read_b128 v[216:219], v152 offset:23552
	s_waitcnt vmcnt(8)
	s_waitcnt lgkmcnt(0)
	s_barrier
	s_setprio 1
	s_waitcnt lgkmcnt(0)
	v_mfma_f32_16x16x32_bf16 v[62:65], v[144:147], v[178:181], v[62:65]
	v_mfma_f32_16x16x32_bf16 v[58:61], v[154:157], v[178:181], v[58:61]
	v_mfma_f32_16x16x32_bf16 v[46:49], v[144:147], v[186:189], v[46:49]
	v_mfma_f32_16x16x32_bf16 v[42:45], v[154:157], v[186:189], v[42:45]
	v_mfma_f32_16x16x32_bf16 v[30:33], v[144:147], v[204:207], v[30:33]
	v_mfma_f32_16x16x32_bf16 v[26:29], v[154:157], v[204:207], v[26:29]
	v_mfma_f32_16x16x32_bf16 v[14:17], v[144:147], v[212:215], v[14:17]
	v_mfma_f32_16x16x32_bf16 v[10:13], v[154:157], v[212:215], v[10:13]
	v_mfma_f32_16x16x32_bf16 v[62:65], v[148:151], v[182:185], v[62:65]
	v_mfma_f32_16x16x32_bf16 v[58:61], v[158:161], v[182:185], v[58:61]
	v_mfma_f32_16x16x32_bf16 v[46:49], v[148:151], v[190:193], v[46:49]
	v_mfma_f32_16x16x32_bf16 v[42:45], v[158:161], v[190:193], v[42:45]
	v_mfma_f32_16x16x32_bf16 v[30:33], v[148:151], v[208:211], v[30:33]
	v_mfma_f32_16x16x32_bf16 v[26:29], v[158:161], v[208:211], v[26:29]
	v_mfma_f32_16x16x32_bf16 v[14:17], v[148:151], v[216:219], v[14:17]
	v_mfma_f32_16x16x32_bf16 v[10:13], v[158:161], v[216:219], v[10:13]
	s_setprio 0
	s_setprio 1
	v_mfma_f32_16x16x32_bf16 v[54:57], v[162:165], v[178:181], v[54:57]
	v_mfma_f32_16x16x32_bf16 v[50:53], v[170:173], v[178:181], v[50:53]
	v_mfma_f32_16x16x32_bf16 v[38:41], v[162:165], v[186:189], v[38:41]
	v_mfma_f32_16x16x32_bf16 v[34:37], v[170:173], v[186:189], v[34:37]
	v_mfma_f32_16x16x32_bf16 v[22:25], v[162:165], v[204:207], v[22:25]
	v_mfma_f32_16x16x32_bf16 v[18:21], v[170:173], v[204:207], v[18:21]
	v_mfma_f32_16x16x32_bf16 v[6:9], v[162:165], v[212:215], v[6:9]
	v_mfma_f32_16x16x32_bf16 v[2:5], v[170:173], v[212:215], v[2:5]
	v_mfma_f32_16x16x32_bf16 v[54:57], v[166:169], v[182:185], v[54:57]
	v_mfma_f32_16x16x32_bf16 v[50:53], v[174:177], v[182:185], v[50:53]
	v_mfma_f32_16x16x32_bf16 v[38:41], v[166:169], v[190:193], v[38:41]
	v_mfma_f32_16x16x32_bf16 v[34:37], v[174:177], v[190:193], v[34:37]
	v_mfma_f32_16x16x32_bf16 v[22:25], v[166:169], v[208:211], v[22:25]
	v_mfma_f32_16x16x32_bf16 v[18:21], v[174:177], v[208:211], v[18:21]
	v_mfma_f32_16x16x32_bf16 v[6:9], v[166:169], v[216:219], v[6:9]
	v_mfma_f32_16x16x32_bf16 v[2:5], v[174:177], v[216:219], v[2:5]
	s_setprio 0
	s_barrier
	s_add_i32 s18, 0, 0x18000
	s_add_i32 s19, 0, 0x1c000
	s_add_u32 s0, s70, 0x80000
	s_addc_u32 s1, s71, 0
	s_mov_b32 m0, s33
	v_lshl_add_u64 v[228:229], s[0:1], 0, v[194:195]
	global_load_lds_dwordx4 v[228:229], off
	v_lshl_add_u64 v[228:229], s[0:1], 0, v[130:131]
	s_mov_b32 m0, s40
	s_nop 0
	global_load_lds_dwordx4 v[228:229], off
	v_add_u32_e32 v153, s18, v1
	ds_read_b128 v[144:147], v153
	ds_read_b128 v[148:151], v153 offset:1024
	ds_read_b128 v[154:157], v153 offset:2048
	ds_read_b128 v[158:161], v153 offset:3072
	v_add_u32_e32 v153, s19, v1
	ds_read_b128 v[162:165], v153
	ds_read_b128 v[166:169], v153 offset:1024
	ds_read_b128 v[170:173], v153 offset:2048
	ds_read_b128 v[174:177], v153 offset:3072
	ds_read_b128 v[178:181], v152 offset:32768
	ds_read_b128 v[182:185], v152 offset:33792
	ds_read_b128 v[186:189], v152 offset:34816
	ds_read_b128 v[190:193], v152 offset:35840
	ds_read_b128 v[204:207], v152 offset:36864
	ds_read_b128 v[208:211], v152 offset:37888
	ds_read_b128 v[212:215], v152 offset:38912
	ds_read_b128 v[216:219], v152 offset:39936
	s_waitcnt vmcnt(8)
	s_waitcnt lgkmcnt(0)
	s_barrier
	s_setprio 1
	s_waitcnt lgkmcnt(0)
	v_mfma_f32_16x16x32_bf16 v[126:129], v[144:147], v[178:181], v[126:129]
	v_mfma_f32_16x16x32_bf16 v[122:125], v[154:157], v[178:181], v[122:125]
	v_mfma_f32_16x16x32_bf16 v[110:113], v[144:147], v[186:189], v[110:113]
	v_mfma_f32_16x16x32_bf16 v[106:109], v[154:157], v[186:189], v[106:109]
	v_mfma_f32_16x16x32_bf16 v[94:97], v[144:147], v[204:207], v[94:97]
	v_mfma_f32_16x16x32_bf16 v[90:93], v[154:157], v[204:207], v[90:93]
	v_mfma_f32_16x16x32_bf16 v[78:81], v[144:147], v[212:215], v[78:81]
	v_mfma_f32_16x16x32_bf16 v[74:77], v[154:157], v[212:215], v[74:77]
	v_mfma_f32_16x16x32_bf16 v[126:129], v[148:151], v[182:185], v[126:129]
	v_mfma_f32_16x16x32_bf16 v[122:125], v[158:161], v[182:185], v[122:125]
	v_mfma_f32_16x16x32_bf16 v[110:113], v[148:151], v[190:193], v[110:113]
	v_mfma_f32_16x16x32_bf16 v[106:109], v[158:161], v[190:193], v[106:109]
	v_mfma_f32_16x16x32_bf16 v[94:97], v[148:151], v[208:211], v[94:97]
	v_mfma_f32_16x16x32_bf16 v[90:93], v[158:161], v[208:211], v[90:93]
	v_mfma_f32_16x16x32_bf16 v[78:81], v[148:151], v[216:219], v[78:81]
	v_mfma_f32_16x16x32_bf16 v[74:77], v[158:161], v[216:219], v[74:77]
	s_setprio 0
	s_setprio 1
	v_mfma_f32_16x16x32_bf16 v[118:121], v[162:165], v[178:181], v[118:121]
	v_mfma_f32_16x16x32_bf16 v[114:117], v[170:173], v[178:181], v[114:117]
	v_mfma_f32_16x16x32_bf16 v[102:105], v[162:165], v[186:189], v[102:105]
	v_mfma_f32_16x16x32_bf16 v[98:101], v[170:173], v[186:189], v[98:101]
	v_mfma_f32_16x16x32_bf16 v[86:89], v[162:165], v[204:207], v[86:89]
	v_mfma_f32_16x16x32_bf16 v[82:85], v[170:173], v[204:207], v[82:85]
	v_mfma_f32_16x16x32_bf16 v[70:73], v[162:165], v[212:215], v[70:73]
	v_mfma_f32_16x16x32_bf16 v[66:69], v[170:173], v[212:215], v[66:69]
	v_mfma_f32_16x16x32_bf16 v[118:121], v[166:169], v[182:185], v[118:121]
	v_mfma_f32_16x16x32_bf16 v[114:117], v[174:177], v[182:185], v[114:117]
	v_mfma_f32_16x16x32_bf16 v[102:105], v[166:169], v[190:193], v[102:105]
	v_mfma_f32_16x16x32_bf16 v[98:101], v[174:177], v[190:193], v[98:101]
	v_mfma_f32_16x16x32_bf16 v[86:89], v[166:169], v[208:211], v[86:89]
	v_mfma_f32_16x16x32_bf16 v[82:85], v[174:177], v[208:211], v[82:85]
	v_mfma_f32_16x16x32_bf16 v[70:73], v[166:169], v[216:219], v[70:73]
	v_mfma_f32_16x16x32_bf16 v[66:69], v[174:177], v[216:219], v[66:69]
	s_setprio 0
	s_barrier
	s_add_i32 s0, s18, s28
	v_lshl_add_u64 v[220:221], v[220:221], 0, s[82:83]
	s_mov_b32 m0, s0
	s_nop 0
	global_load_lds_dwordx4 v[220:221], off
	s_add_i32 m0, s0, 0x2000
	s_add_u32 s0, s64, 0x80080
	v_lshl_add_u64 v[220:221], v[222:223], 0, s[82:83]
	s_addc_u32 s1, s65, 0
	s_add_i32 s18, s19, s28
	global_load_lds_dwordx4 v[220:221], off
	v_lshl_add_u64 v[220:221], s[0:1], 0, v[194:195]
	s_mov_b32 m0, s18
	s_nop 0
	global_load_lds_dwordx4 v[220:221], off
	v_lshl_add_u64 v[220:221], s[0:1], 0, v[130:131]
	s_add_i32 m0, s18, 0x2000
	s_nop 0
	global_load_lds_dwordx4 v[220:221], off
	v_lshl_add_u64 v[220:221], v[224:225], 0, s[82:83]
	s_mov_b32 m0, s54
	s_nop 0
	global_load_lds_dwordx4 v[220:221], off
	v_lshl_add_u64 v[220:221], v[226:227], 0, s[82:83]
	s_mov_b32 m0, s57
	s_nop 0
	global_load_lds_dwordx4 v[220:221], off
	ds_read_b128 v[178:181], v152 offset:49152
	ds_read_b128 v[182:185], v152 offset:50176
	ds_read_b128 v[186:189], v152 offset:51200
	ds_read_b128 v[190:193], v152 offset:52224
	ds_read_b128 v[204:207], v152 offset:53248
	ds_read_b128 v[208:211], v152 offset:54272
	ds_read_b128 v[212:215], v152 offset:55296
	ds_read_b128 v[216:219], v152 offset:56320
	s_waitcnt vmcnt(8)
	s_waitcnt lgkmcnt(0)
	s_barrier
	s_setprio 1
	s_waitcnt lgkmcnt(0)
	v_mfma_f32_16x16x32_bf16 v[62:65], v[144:147], v[178:181], v[62:65]
	v_mfma_f32_16x16x32_bf16 v[58:61], v[154:157], v[178:181], v[58:61]
	v_mfma_f32_16x16x32_bf16 v[46:49], v[144:147], v[186:189], v[46:49]
	v_mfma_f32_16x16x32_bf16 v[42:45], v[154:157], v[186:189], v[42:45]
	v_mfma_f32_16x16x32_bf16 v[30:33], v[144:147], v[204:207], v[30:33]
	v_mfma_f32_16x16x32_bf16 v[26:29], v[154:157], v[204:207], v[26:29]
	v_mfma_f32_16x16x32_bf16 v[14:17], v[144:147], v[212:215], v[14:17]
	v_mfma_f32_16x16x32_bf16 v[10:13], v[154:157], v[212:215], v[10:13]
	v_mfma_f32_16x16x32_bf16 v[62:65], v[148:151], v[182:185], v[62:65]
	v_mfma_f32_16x16x32_bf16 v[58:61], v[158:161], v[182:185], v[58:61]
	v_mfma_f32_16x16x32_bf16 v[46:49], v[148:151], v[190:193], v[46:49]
	v_mfma_f32_16x16x32_bf16 v[42:45], v[158:161], v[190:193], v[42:45]
	v_mfma_f32_16x16x32_bf16 v[30:33], v[148:151], v[208:211], v[30:33]
	v_mfma_f32_16x16x32_bf16 v[26:29], v[158:161], v[208:211], v[26:29]
	v_mfma_f32_16x16x32_bf16 v[14:17], v[148:151], v[216:219], v[14:17]
	v_mfma_f32_16x16x32_bf16 v[10:13], v[158:161], v[216:219], v[10:13]
	s_setprio 0
	s_setprio 1
	v_mfma_f32_16x16x32_bf16 v[54:57], v[162:165], v[178:181], v[54:57]
	v_mfma_f32_16x16x32_bf16 v[50:53], v[170:173], v[178:181], v[50:53]
	v_mfma_f32_16x16x32_bf16 v[38:41], v[162:165], v[186:189], v[38:41]
	v_mfma_f32_16x16x32_bf16 v[34:37], v[170:173], v[186:189], v[34:37]
	v_mfma_f32_16x16x32_bf16 v[22:25], v[162:165], v[204:207], v[22:25]
	v_mfma_f32_16x16x32_bf16 v[18:21], v[170:173], v[204:207], v[18:21]
	v_mfma_f32_16x16x32_bf16 v[6:9], v[162:165], v[212:215], v[6:9]
	v_mfma_f32_16x16x32_bf16 v[2:5], v[170:173], v[212:215], v[2:5]
	v_mfma_f32_16x16x32_bf16 v[54:57], v[166:169], v[182:185], v[54:57]
	v_mfma_f32_16x16x32_bf16 v[50:53], v[174:177], v[182:185], v[50:53]
	v_mfma_f32_16x16x32_bf16 v[38:41], v[166:169], v[190:193], v[38:41]
	v_mfma_f32_16x16x32_bf16 v[34:37], v[174:177], v[190:193], v[34:37]
	v_mfma_f32_16x16x32_bf16 v[22:25], v[166:169], v[208:211], v[22:25]
	v_mfma_f32_16x16x32_bf16 v[18:21], v[174:177], v[208:211], v[18:21]
	v_mfma_f32_16x16x32_bf16 v[6:9], v[166:169], v[216:219], v[6:9]
	v_mfma_f32_16x16x32_bf16 v[2:5], v[174:177], v[216:219], v[2:5]
	s_setprio 0
	s_barrier
	s_add_i32 s76, s76, 2
	s_add_u32 s62, s62, 0x100
	s_addc_u32 s63, s63, 0
	s_add_u32 s53, s53, 0x100
	s_addc_u32 s58, s58, 0
	s_cmp_gt_u32 s76, 29
	s_cbranch_scc1 .LBB0_584

.LBB0_645:
	s_add_u32 s64, s8, 0x100
	s_addc_u32 s65, s9, 0
	s_and_b64 s[0:1], s[70:71], exec
	s_cselect_b32 s77, s63, s65
	s_cselect_b32 s76, s62, s64
	s_cselect_b32 s71, s85, s23
	s_cselect_b32 s70, s84, s7
	s_add_i32 s0, 0, 0x10000
	s_add_i32 s18, 0, 0x14000
	v_lshl_add_u64 v[218:219], s[8:9], 0, v[206:207]
	s_add_i32 m0, s29, 0xc000
	s_nop 0
	global_load_lds_dwordx4 v[218:219], off
	v_lshl_add_u64 v[218:219], s[8:9], 0, v[208:209]
	s_add_i32 m0, s29, 0xe000
	s_nop 0
	global_load_lds_dwordx4 v[218:219], off
	v_add_u32_e32 v106, s0, v1
	v_add_u32_e32 v154, s18, v1
	ds_read_b128 v[70:73], v106
	ds_read_b128 v[82:85], v106 offset:1024
	ds_read_b128 v[94:97], v106 offset:2048
	ds_read_b128 v[106:109], v106 offset:3072
	ds_read_b128 v[118:121], v154
	ds_read_b128 v[130:133], v154 offset:1024
	ds_read_b128 v[142:145], v154 offset:2048
	ds_read_b128 v[154:157], v154 offset:3072
	ds_read_b128 v[158:161], v237
	ds_read_b128 v[170:173], v237 offset:1024
	ds_read_b128 v[174:177], v237 offset:2048
	ds_read_b128 v[178:181], v237 offset:3072
	ds_read_b128 v[182:185], v237 offset:4096
	ds_read_b128 v[186:189], v237 offset:5120
	ds_read_b128 v[210:213], v237 offset:6144
	ds_read_b128 v[214:217], v237 offset:7168
	s_waitcnt vmcnt(8)
	s_waitcnt lgkmcnt(0)
	s_barrier
	s_setprio 1
	s_waitcnt lgkmcnt(0)
	v_mfma_f32_16x16x32_bf16 v[166:169], v[70:73], v[158:161], v[166:169]
	v_mfma_f32_16x16x32_bf16 v[162:165], v[94:97], v[158:161], v[162:165]
	v_mfma_f32_16x16x32_bf16 v[138:141], v[70:73], v[174:177], v[138:141]
	v_mfma_f32_16x16x32_bf16 v[134:137], v[94:97], v[174:177], v[134:137]
	v_mfma_f32_16x16x32_bf16 v[114:117], v[70:73], v[182:185], v[114:117]
	v_mfma_f32_16x16x32_bf16 v[110:113], v[94:97], v[182:185], v[110:113]
	v_mfma_f32_16x16x32_bf16 v[90:93], v[70:73], v[210:213], v[90:93]
	v_mfma_f32_16x16x32_bf16 v[86:89], v[94:97], v[210:213], v[86:89]
	v_mfma_f32_16x16x32_bf16 v[166:169], v[82:85], v[170:173], v[166:169]
	v_mfma_f32_16x16x32_bf16 v[162:165], v[106:109], v[170:173], v[162:165]
	v_mfma_f32_16x16x32_bf16 v[138:141], v[82:85], v[178:181], v[138:141]
	v_mfma_f32_16x16x32_bf16 v[134:137], v[106:109], v[178:181], v[134:137]
	v_mfma_f32_16x16x32_bf16 v[114:117], v[82:85], v[186:189], v[114:117]
	v_mfma_f32_16x16x32_bf16 v[110:113], v[106:109], v[186:189], v[110:113]
	v_mfma_f32_16x16x32_bf16 v[90:93], v[82:85], v[214:217], v[90:93]
	v_mfma_f32_16x16x32_bf16 v[86:89], v[106:109], v[214:217], v[86:89]
	s_setprio 0
	s_setprio 1
	v_mfma_f32_16x16x32_bf16 v[150:153], v[118:121], v[158:161], v[150:153]
	v_mfma_f32_16x16x32_bf16 v[146:149], v[142:145], v[158:161], v[146:149]
	v_mfma_f32_16x16x32_bf16 v[126:129], v[118:121], v[174:177], v[126:129]
	v_mfma_f32_16x16x32_bf16 v[122:125], v[142:145], v[174:177], v[122:125]
	v_mfma_f32_16x16x32_bf16 v[102:105], v[118:121], v[182:185], v[102:105]
	v_mfma_f32_16x16x32_bf16 v[98:101], v[142:145], v[182:185], v[98:101]
	v_mfma_f32_16x16x32_bf16 v[78:81], v[118:121], v[210:213], v[78:81]
	v_mfma_f32_16x16x32_bf16 v[74:77], v[142:145], v[210:213], v[74:77]
	v_mfma_f32_16x16x32_bf16 v[150:153], v[130:133], v[170:173], v[150:153]
	v_mfma_f32_16x16x32_bf16 v[146:149], v[154:157], v[170:173], v[146:149]
	v_mfma_f32_16x16x32_bf16 v[126:129], v[130:133], v[178:181], v[126:129]
	v_mfma_f32_16x16x32_bf16 v[122:125], v[154:157], v[178:181], v[122:125]
	v_mfma_f32_16x16x32_bf16 v[102:105], v[130:133], v[186:189], v[102:105]
	v_mfma_f32_16x16x32_bf16 v[98:101], v[154:157], v[186:189], v[98:101]
	v_mfma_f32_16x16x32_bf16 v[78:81], v[130:133], v[214:217], v[78:81]
	v_mfma_f32_16x16x32_bf16 v[74:77], v[154:157], v[214:217], v[74:77]
	s_setprio 0
	s_barrier
	s_add_i32 s0, s0, s28
	v_lshl_add_u64 v[218:219], s[70:71], 0, v[192:193]
	s_mov_b32 m0, s0
	s_nop 0
	global_load_lds_dwordx4 v[218:219], off
	s_add_i32 m0, s0, 0x2000
	s_add_u32 s0, s70, 0x160000
	v_lshl_add_u64 v[220:221], s[70:71], 0, v[190:191]
	s_addc_u32 s1, s71, 0
	s_add_i32 s8, s18, s28
	global_load_lds_dwordx4 v[220:221], off
	v_lshl_add_u64 v[222:223], s[0:1], 0, v[192:193]
	s_mov_b32 m0, s8
	v_lshl_add_u64 v[224:225], s[76:77], 0, v[190:191]
	global_load_lds_dwordx4 v[222:223], off
	v_lshl_add_u64 v[222:223], s[0:1], 0, v[190:191]
	s_add_i32 m0, s8, 0x2000
	s_nop 0
	global_load_lds_dwordx4 v[222:223], off
	v_lshl_add_u64 v[222:223], s[76:77], 0, v[192:193]
	s_mov_b32 m0, s29
	s_nop 0
	global_load_lds_dwordx4 v[222:223], off
	s_mov_b32 m0, s31
	s_nop 0
	global_load_lds_dwordx4 v[224:225], off
	ds_read_b128 v[158:161], v237 offset:16384
	ds_read_b128 v[170:173], v237 offset:17408
	ds_read_b128 v[174:177], v237 offset:18432
	ds_read_b128 v[178:181], v237 offset:19456
	ds_read_b128 v[182:185], v237 offset:20480
	ds_read_b128 v[186:189], v237 offset:21504
	ds_read_b128 v[210:213], v237 offset:22528
	ds_read_b128 v[214:217], v237 offset:23552
	s_waitcnt vmcnt(8)
	s_waitcnt lgkmcnt(0)
	s_barrier
	s_setprio 1
	s_waitcnt lgkmcnt(0)
	v_mfma_f32_16x16x32_bf16 v[62:65], v[70:73], v[158:161], v[62:65]
	v_mfma_f32_16x16x32_bf16 v[58:61], v[94:97], v[158:161], v[58:61]
	v_mfma_f32_16x16x32_bf16 v[46:49], v[70:73], v[174:177], v[46:49]
	v_mfma_f32_16x16x32_bf16 v[42:45], v[94:97], v[174:177], v[42:45]
	v_mfma_f32_16x16x32_bf16 v[30:33], v[70:73], v[182:185], v[30:33]
	v_mfma_f32_16x16x32_bf16 v[26:29], v[94:97], v[182:185], v[26:29]
	v_mfma_f32_16x16x32_bf16 v[14:17], v[70:73], v[210:213], v[14:17]
	v_mfma_f32_16x16x32_bf16 v[10:13], v[94:97], v[210:213], v[10:13]
	v_mfma_f32_16x16x32_bf16 v[62:65], v[82:85], v[170:173], v[62:65]
	v_mfma_f32_16x16x32_bf16 v[58:61], v[106:109], v[170:173], v[58:61]
	v_mfma_f32_16x16x32_bf16 v[46:49], v[82:85], v[178:181], v[46:49]
	v_mfma_f32_16x16x32_bf16 v[42:45], v[106:109], v[178:181], v[42:45]
	v_mfma_f32_16x16x32_bf16 v[30:33], v[82:85], v[186:189], v[30:33]
	v_mfma_f32_16x16x32_bf16 v[26:29], v[106:109], v[186:189], v[26:29]
	v_mfma_f32_16x16x32_bf16 v[14:17], v[82:85], v[214:217], v[14:17]
	v_mfma_f32_16x16x32_bf16 v[10:13], v[106:109], v[214:217], v[10:13]
	s_setprio 0
	s_setprio 1
	v_mfma_f32_16x16x32_bf16 v[54:57], v[118:121], v[158:161], v[54:57]
	v_mfma_f32_16x16x32_bf16 v[50:53], v[142:145], v[158:161], v[50:53]
	v_mfma_f32_16x16x32_bf16 v[38:41], v[118:121], v[174:177], v[38:41]
	v_mfma_f32_16x16x32_bf16 v[34:37], v[142:145], v[174:177], v[34:37]
	v_mfma_f32_16x16x32_bf16 v[22:25], v[118:121], v[182:185], v[22:25]
	v_mfma_f32_16x16x32_bf16 v[18:21], v[142:145], v[182:185], v[18:21]
	v_mfma_f32_16x16x32_bf16 v[6:9], v[118:121], v[210:213], v[6:9]
	v_mfma_f32_16x16x32_bf16 v[2:5], v[142:145], v[210:213], v[2:5]
	v_mfma_f32_16x16x32_bf16 v[54:57], v[130:133], v[170:173], v[54:57]
	v_mfma_f32_16x16x32_bf16 v[50:53], v[154:157], v[170:173], v[50:53]
	v_mfma_f32_16x16x32_bf16 v[38:41], v[130:133], v[178:181], v[38:41]
	v_mfma_f32_16x16x32_bf16 v[34:37], v[154:157], v[178:181], v[34:37]
	v_mfma_f32_16x16x32_bf16 v[22:25], v[130:133], v[186:189], v[22:25]
	v_mfma_f32_16x16x32_bf16 v[18:21], v[154:157], v[186:189], v[18:21]
	v_mfma_f32_16x16x32_bf16 v[6:9], v[130:133], v[214:217], v[6:9]
	v_mfma_f32_16x16x32_bf16 v[2:5], v[154:157], v[214:217], v[2:5]
	s_setprio 0
	s_barrier
	s_add_i32 s8, 0, 0x18000
	s_add_i32 s9, 0, 0x1c000
	s_add_u32 s0, s76, 0x160000
	s_addc_u32 s1, s77, 0
	s_mov_b32 m0, s33
	v_lshl_add_u64 v[226:227], s[0:1], 0, v[192:193]
	global_load_lds_dwordx4 v[226:227], off
	v_lshl_add_u64 v[226:227], s[0:1], 0, v[190:191]
	s_mov_b32 m0, s43
	s_nop 0
	global_load_lds_dwordx4 v[226:227], off
	v_add_u32_e32 v106, s8, v1
	v_add_u32_e32 v154, s9, v1
	ds_read_b128 v[70:73], v106
	ds_read_b128 v[82:85], v106 offset:1024
	ds_read_b128 v[94:97], v106 offset:2048
	ds_read_b128 v[106:109], v106 offset:3072
	ds_read_b128 v[118:121], v154
	ds_read_b128 v[130:133], v154 offset:1024
	ds_read_b128 v[142:145], v154 offset:2048
	ds_read_b128 v[154:157], v154 offset:3072
	ds_read_b128 v[158:161], v237 offset:32768
	ds_read_b128 v[170:173], v237 offset:33792
	ds_read_b128 v[174:177], v237 offset:34816
	ds_read_b128 v[178:181], v237 offset:35840
	ds_read_b128 v[182:185], v237 offset:36864
	ds_read_b128 v[186:189], v237 offset:37888
	ds_read_b128 v[210:213], v237 offset:38912
	ds_read_b128 v[214:217], v237 offset:39936
	s_waitcnt vmcnt(8)
	s_waitcnt lgkmcnt(0)
	s_barrier
	s_setprio 1
	s_waitcnt lgkmcnt(0)
	v_mfma_f32_16x16x32_bf16 v[166:169], v[70:73], v[158:161], v[166:169]
	v_mfma_f32_16x16x32_bf16 v[162:165], v[94:97], v[158:161], v[162:165]
	v_mfma_f32_16x16x32_bf16 v[138:141], v[70:73], v[174:177], v[138:141]
	v_mfma_f32_16x16x32_bf16 v[134:137], v[94:97], v[174:177], v[134:137]
	v_mfma_f32_16x16x32_bf16 v[114:117], v[70:73], v[182:185], v[114:117]
	v_mfma_f32_16x16x32_bf16 v[110:113], v[94:97], v[182:185], v[110:113]
	v_mfma_f32_16x16x32_bf16 v[90:93], v[70:73], v[210:213], v[90:93]
	v_mfma_f32_16x16x32_bf16 v[86:89], v[94:97], v[210:213], v[86:89]
	v_mfma_f32_16x16x32_bf16 v[166:169], v[82:85], v[170:173], v[166:169]
	v_mfma_f32_16x16x32_bf16 v[162:165], v[106:109], v[170:173], v[162:165]
	v_mfma_f32_16x16x32_bf16 v[138:141], v[82:85], v[178:181], v[138:141]
	v_mfma_f32_16x16x32_bf16 v[134:137], v[106:109], v[178:181], v[134:137]
	v_mfma_f32_16x16x32_bf16 v[114:117], v[82:85], v[186:189], v[114:117]
	v_mfma_f32_16x16x32_bf16 v[110:113], v[106:109], v[186:189], v[110:113]
	v_mfma_f32_16x16x32_bf16 v[90:93], v[82:85], v[214:217], v[90:93]
	v_mfma_f32_16x16x32_bf16 v[86:89], v[106:109], v[214:217], v[86:89]
	s_setprio 0
	s_setprio 1
	v_mfma_f32_16x16x32_bf16 v[150:153], v[118:121], v[158:161], v[150:153]
	v_mfma_f32_16x16x32_bf16 v[146:149], v[142:145], v[158:161], v[146:149]
	v_mfma_f32_16x16x32_bf16 v[126:129], v[118:121], v[174:177], v[126:129]
	v_mfma_f32_16x16x32_bf16 v[122:125], v[142:145], v[174:177], v[122:125]
	v_mfma_f32_16x16x32_bf16 v[102:105], v[118:121], v[182:185], v[102:105]
	v_mfma_f32_16x16x32_bf16 v[98:101], v[142:145], v[182:185], v[98:101]
	v_mfma_f32_16x16x32_bf16 v[78:81], v[118:121], v[210:213], v[78:81]
	v_mfma_f32_16x16x32_bf16 v[74:77], v[142:145], v[210:213], v[74:77]
	v_mfma_f32_16x16x32_bf16 v[150:153], v[130:133], v[170:173], v[150:153]
	v_mfma_f32_16x16x32_bf16 v[146:149], v[154:157], v[170:173], v[146:149]
	v_mfma_f32_16x16x32_bf16 v[126:129], v[130:133], v[178:181], v[126:129]
	v_mfma_f32_16x16x32_bf16 v[122:125], v[154:157], v[178:181], v[122:125]
	v_mfma_f32_16x16x32_bf16 v[102:105], v[130:133], v[186:189], v[102:105]
	v_mfma_f32_16x16x32_bf16 v[98:101], v[154:157], v[186:189], v[98:101]
	v_mfma_f32_16x16x32_bf16 v[78:81], v[130:133], v[214:217], v[78:81]
	v_mfma_f32_16x16x32_bf16 v[74:77], v[154:157], v[214:217], v[74:77]
	s_setprio 0
	s_barrier
	s_add_i32 s0, s8, s28
	v_lshl_add_u64 v[218:219], v[218:219], 0, s[82:83]
	s_mov_b32 m0, s0
	s_nop 0
	global_load_lds_dwordx4 v[218:219], off
	s_add_i32 m0, s0, 0x2000
	s_add_u32 s0, s70, 0x160080
	v_lshl_add_u64 v[218:219], v[220:221], 0, s[82:83]
	s_addc_u32 s1, s71, 0
	s_add_i32 s8, s9, s28
	global_load_lds_dwordx4 v[218:219], off
	v_lshl_add_u64 v[218:219], s[0:1], 0, v[192:193]
	s_mov_b32 m0, s8
	s_nop 0
	global_load_lds_dwordx4 v[218:219], off
	v_lshl_add_u64 v[218:219], s[0:1], 0, v[190:191]
	s_add_i32 m0, s8, 0x2000
	s_nop 0
	global_load_lds_dwordx4 v[218:219], off
	v_lshl_add_u64 v[218:219], v[222:223], 0, s[82:83]
	s_mov_b32 m0, s68
	s_nop 0
	global_load_lds_dwordx4 v[218:219], off
	v_lshl_add_u64 v[218:219], v[224:225], 0, s[82:83]
	s_mov_b32 m0, s79
	s_nop 0
	global_load_lds_dwordx4 v[218:219], off
	ds_read_b128 v[158:161], v237 offset:49152
	ds_read_b128 v[170:173], v237 offset:50176
	ds_read_b128 v[174:177], v237 offset:51200
	ds_read_b128 v[178:181], v237 offset:52224
	ds_read_b128 v[182:185], v237 offset:53248
	ds_read_b128 v[186:189], v237 offset:54272
	ds_read_b128 v[210:213], v237 offset:55296
	ds_read_b128 v[214:217], v237 offset:56320
	s_waitcnt vmcnt(8)
	s_waitcnt lgkmcnt(0)
	s_barrier
	s_setprio 1
	s_waitcnt lgkmcnt(0)
	v_mfma_f32_16x16x32_bf16 v[62:65], v[70:73], v[158:161], v[62:65]
	v_mfma_f32_16x16x32_bf16 v[58:61], v[94:97], v[158:161], v[58:61]
	v_mfma_f32_16x16x32_bf16 v[46:49], v[70:73], v[174:177], v[46:49]
	v_mfma_f32_16x16x32_bf16 v[42:45], v[94:97], v[174:177], v[42:45]
	v_mfma_f32_16x16x32_bf16 v[30:33], v[70:73], v[182:185], v[30:33]
	v_mfma_f32_16x16x32_bf16 v[26:29], v[94:97], v[182:185], v[26:29]
	v_mfma_f32_16x16x32_bf16 v[14:17], v[70:73], v[210:213], v[14:17]
	v_mfma_f32_16x16x32_bf16 v[10:13], v[94:97], v[210:213], v[10:13]
	v_mfma_f32_16x16x32_bf16 v[62:65], v[82:85], v[170:173], v[62:65]
	v_mfma_f32_16x16x32_bf16 v[58:61], v[106:109], v[170:173], v[58:61]
	v_mfma_f32_16x16x32_bf16 v[46:49], v[82:85], v[178:181], v[46:49]
	v_mfma_f32_16x16x32_bf16 v[42:45], v[106:109], v[178:181], v[42:45]
	v_mfma_f32_16x16x32_bf16 v[30:33], v[82:85], v[186:189], v[30:33]
	v_mfma_f32_16x16x32_bf16 v[26:29], v[106:109], v[186:189], v[26:29]
	v_mfma_f32_16x16x32_bf16 v[14:17], v[82:85], v[214:217], v[14:17]
	v_mfma_f32_16x16x32_bf16 v[10:13], v[106:109], v[214:217], v[10:13]
	s_setprio 0
	s_setprio 1
	v_mfma_f32_16x16x32_bf16 v[54:57], v[118:121], v[158:161], v[54:57]
	v_mfma_f32_16x16x32_bf16 v[50:53], v[142:145], v[158:161], v[50:53]
	v_mfma_f32_16x16x32_bf16 v[38:41], v[118:121], v[174:177], v[38:41]
	v_mfma_f32_16x16x32_bf16 v[34:37], v[142:145], v[174:177], v[34:37]
	v_mfma_f32_16x16x32_bf16 v[22:25], v[118:121], v[182:185], v[22:25]
	v_mfma_f32_16x16x32_bf16 v[18:21], v[142:145], v[182:185], v[18:21]
	v_mfma_f32_16x16x32_bf16 v[6:9], v[118:121], v[210:213], v[6:9]
	v_mfma_f32_16x16x32_bf16 v[2:5], v[142:145], v[210:213], v[2:5]
	v_mfma_f32_16x16x32_bf16 v[54:57], v[130:133], v[170:173], v[54:57]
	v_mfma_f32_16x16x32_bf16 v[50:53], v[154:157], v[170:173], v[50:53]
	v_mfma_f32_16x16x32_bf16 v[38:41], v[130:133], v[178:181], v[38:41]
	v_mfma_f32_16x16x32_bf16 v[34:37], v[154:157], v[178:181], v[34:37]
	v_mfma_f32_16x16x32_bf16 v[22:25], v[130:133], v[186:189], v[22:25]
	v_mfma_f32_16x16x32_bf16 v[18:21], v[154:157], v[186:189], v[18:21]
	v_mfma_f32_16x16x32_bf16 v[6:9], v[130:133], v[214:217], v[6:9]
	v_mfma_f32_16x16x32_bf16 v[2:5], v[154:157], v[214:217], v[2:5]
	s_setprio 0
	s_barrier
	s_add_i32 s41, s41, 2
	s_add_u32 s7, s7, 0x100
	s_addc_u32 s23, s23, 0
	s_cmpk_gt_u32 s41, 0x55
	s_mov_b64 s[8:9], s[64:65]
	s_cbranch_scc1 .LBB0_648
